# filter-item load hoisting, hy_final batched loads, shortconv 1-iteration prefetch
# speedup vs baseline: 1.0372x; 1.0143x over previous
; __device__ __forceinline__ void prep_filter_item(const Params& p, int l, int it, char* smem, int wvi) {
;     ...
;     const float* W = p.fw1 + (size_t)l * 33 * 64; const float bb = p.fb1[l * 64 + u];
; #pragma unroll 1
;     for (int q = 0; q < 4; ++q) {
;       const int ps = pg * 4 + q; float a = bb;
;       for (int k = 0; k < 33; ++k) a += sF[ps * 33 + k] * W[k * 64 + u];
;       sH1[ps * 64 + u] = sinf(fr * a);
;     }
.LBB0_152:
	v_lshl_add_u64 v[18:19], v[4:5], 0, s[2:3]
	v_add_co_u32_e32 v18, vcc, 0x2000, v18
	ds_read2_b32 v[16:17], v13 offset1:1
	s_nop 0
	v_addc_co_u32_e32 v19, vcc, 0, v19, vcc
	global_load_dword v80, v[18:19], off offset:256
	global_load_dword v81, v[18:19], off offset:512
	global_load_dword v82, v[18:19], off offset:768
	global_load_dword v83, v[18:19], off offset:1024
	global_load_dword v84, v[18:19], off offset:1280
	global_load_dword v85, v[18:19], off offset:1536
	global_load_dword v86, v[18:19], off offset:1792
	global_load_dword v87, v[18:19], off offset:2048
	global_load_dword v88, v[18:19], off offset:2304
	global_load_dword v89, v[18:19], off offset:2560
	global_load_dword v90, v[18:19], off offset:2816
	s_add_u32 s2, s2, 0xb00
	s_addc_u32 s3, s3, 0
	s_cmpk_eq_i32 s2, 0x2100
	s_waitcnt vmcnt(10) lgkmcnt(0)
	v_fmac_f32_e32 v14, v16, v80
	s_waitcnt vmcnt(9)
	v_fmac_f32_e32 v14, v17, v81
	ds_read2_b32 v[16:17], v13 offset0:2 offset1:3
	s_waitcnt vmcnt(8) lgkmcnt(0)
	v_fmac_f32_e32 v14, v16, v82
	s_waitcnt vmcnt(7)
	v_fmac_f32_e32 v14, v17, v83
	ds_read2_b32 v[16:17], v13 offset0:4 offset1:5
	s_waitcnt vmcnt(6) lgkmcnt(0)
	v_fmac_f32_e32 v14, v16, v84
	s_waitcnt vmcnt(5)
	v_fmac_f32_e32 v14, v17, v85
	ds_read2_b32 v[16:17], v13 offset0:6 offset1:7
	s_waitcnt vmcnt(4) lgkmcnt(0)
	v_fmac_f32_e32 v14, v16, v86
	s_waitcnt vmcnt(3)
	v_fmac_f32_e32 v14, v17, v87
	ds_read2_b32 v[16:17], v13 offset0:8 offset1:9
	s_waitcnt vmcnt(2) lgkmcnt(0)
	v_fmac_f32_e32 v14, v16, v88
	s_waitcnt vmcnt(1)
	v_fmac_f32_e32 v14, v17, v89
	ds_read_b32 v15, v13 offset:40
	v_add_u32_e32 v13, 44, v13
	s_waitcnt vmcnt(0) lgkmcnt(0)
	v_fmac_f32_e32 v14, v15, v90
	s_cbranch_scc0 .LBB0_152
	v_mul_f32_e32 v13, v7, v14
	v_and_b32_e32 v14, 0x7fffffff, v13
	v_cmp_nlt_f32_e64 s[2:3], |v13|, s24
	s_and_saveexec_b64 s[6:7], s[2:3]
	s_xor_b64 s[2:3], exec, s[6:7]
	s_cbranch_execz .LBB0_155
	v_lshrrev_b32_e32 v15, 23, v14
	v_add_u32_e32 v15, 0xffffff88, v15
	v_cmp_lt_u32_e32 vcc, 63, v15
	s_nop 1
	v_cndmask_b32_e32 v16, 0, v203, vcc
	v_add_u32_e32 v15, v16, v15
	v_cmp_lt_u32_e64 s[6:7], 31, v15
	s_nop 1
	v_cndmask_b32_e64 v16, 0, v204, s[6:7]
	v_add_u32_e32 v15, v16, v15
	v_cmp_lt_u32_e64 s[8:9], 31, v15
	s_nop 1
	v_cndmask_b32_e64 v16, 0, v204, s[8:9]
	v_add_u32_e32 v15, v16, v15
	v_and_b32_e32 v16, 0x7fffff, v14
	v_or_b32_e32 v28, 0x800000, v16
	v_mad_u64_u32 v[16:17], s[10:11], v28, s25, 0
	v_mov_b32_e32 v176, v17
	v_mad_u64_u32 v[18:19], s[10:11], v28, s26, v[176:177]
	v_mov_b32_e32 v176, v19
	v_mad_u64_u32 v[20:21], s[10:11], v28, s27, v[176:177]
	v_mov_b32_e32 v176, v21
	v_mad_u64_u32 v[22:23], s[10:11], v28, s34, v[176:177]
	v_mov_b32_e32 v176, v23
	v_mad_u64_u32 v[24:25], s[10:11], v28, s35, v[176:177]
	v_mov_b32_e32 v176, v25
	v_mad_u64_u32 v[26:27], s[10:11], v28, s36, v[176:177]
	v_mov_b32_e32 v176, v27
	v_mad_u64_u32 v[28:29], s[10:11], v28, s37, v[176:177]
	v_cndmask_b32_e32 v17, v26, v22, vcc
	v_cndmask_b32_e32 v19, v28, v24, vcc
	v_cndmask_b32_e32 v23, v29, v26, vcc
	v_cndmask_b32_e64 v21, v19, v17, s[6:7]
	v_cndmask_b32_e64 v19, v23, v19, s[6:7]
	v_cndmask_b32_e32 v23, v24, v20, vcc
	v_cndmask_b32_e64 v17, v17, v23, s[6:7]
	v_cndmask_b32_e64 v19, v19, v21, s[8:9]
	v_cndmask_b32_e64 v21, v21, v17, s[8:9]
	v_sub_u32_e32 v24, 32, v15
	v_alignbit_b32 v25, v19, v21, v24
	v_cmp_eq_u32_e64 s[10:11], 0, v15
	v_cndmask_b32_e32 v18, v22, v18, vcc
	v_cndmask_b32_e32 v16, v20, v16, vcc
	v_cndmask_b32_e64 v15, v25, v19, s[10:11]
	v_cndmask_b32_e64 v19, v23, v18, s[6:7]
	v_cndmask_b32_e64 v17, v17, v19, s[8:9]
	v_alignbit_b32 v22, v21, v17, v24
	v_cndmask_b32_e64 v21, v22, v21, s[10:11]
	v_bfe_u32 v25, v15, 29, 1
	v_cndmask_b32_e64 v16, v18, v16, s[6:7]
	v_alignbit_b32 v22, v15, v21, 30
	v_sub_u32_e32 v26, 0, v25
	v_cndmask_b32_e64 v16, v19, v16, s[8:9]
	v_xor_b32_e32 v22, v22, v26
	v_alignbit_b32 v18, v17, v16, v24
	v_cndmask_b32_e64 v17, v18, v17, s[10:11]
	v_ffbh_u32_e32 v19, v22
	v_alignbit_b32 v18, v21, v17, 30
	v_min_u32_e32 v19, 32, v19
	v_alignbit_b32 v16, v17, v16, 30
	v_xor_b32_e32 v18, v18, v26
	v_sub_u32_e32 v20, 31, v19
	v_xor_b32_e32 v16, v16, v26
	v_alignbit_b32 v21, v22, v18, v20
	v_alignbit_b32 v16, v18, v16, v20
	v_alignbit_b32 v17, v21, v16, 9
	v_ffbh_u32_e32 v18, v17
	v_min_u32_e32 v18, 32, v18
	v_lshrrev_b32_e32 v23, 29, v15
	v_not_b32_e32 v20, v18
	v_alignbit_b32 v16, v17, v16, v20
	v_lshlrev_b32_e32 v17, 31, v23
	v_or_b32_e32 v20, 0x33000000, v17
	v_add_lshl_u32 v18, v18, v19, 23
	v_lshrrev_b32_e32 v16, 9, v16
	v_sub_u32_e32 v18, v20, v18
	v_or_b32_e32 v17, 0.5, v17
	v_lshlrev_b32_e32 v19, 23, v19
	v_or_b32_e32 v16, v18, v16
	v_lshrrev_b32_e32 v18, 9, v21
	v_sub_u32_e32 v17, v17, v19
	v_or_b32_e32 v17, v18, v17
	v_mul_f32_e32 v18, 0x3fc90fda, v17
	v_fma_f32 v19, v17, s38, -v18
	v_fmac_f32_e32 v19, 0x33a22168, v17
	v_fmac_f32_e32 v19, 0x3fc90fda, v16
	v_lshrrev_b32_e32 v15, 30, v15
	v_add_f32_e32 v16, v18, v19
	v_add_u32_e32 v15, v25, v15

; __device__ __forceinline__ void prep_filter_item(const Params& p, int l, int it, char* smem, int wvi) {
;     ...
;     const float* W = p.fw2 + (size_t)l * 64 * 64; const float bb = p.fb2[l * 64 + u];
; #pragma unroll 1
;     for (int q = 0; q < 4; ++q) {
;       const int ps = pg * 4 + q; float a = bb;
;       for (int k = 0; k < 64; ++k) a += sH1[ps * 64 + k] * W[k * 64 + u];
;       sH2[ps * 64 + u] = sinf(fr * a);
;     }
.LBB0_160:
	v_lshl_add_u64 v[34:35], v[4:5], 0, s[2:3]
	v_add_co_u32_e32 v34, vcc, 0x4000, v34
	ds_read_b128 v[16:19], v14
	ds_read_b128 v[20:23], v14 offset:16
	ds_read_b128 v[24:27], v14 offset:32
	ds_read_b128 v[28:31], v14 offset:48
	v_addc_co_u32_e32 v35, vcc, 0, v35, vcc
	global_load_dword v80, v[34:35], off
	global_load_dword v81, v[34:35], off offset:256
	global_load_dword v82, v[34:35], off offset:512
	global_load_dword v83, v[34:35], off offset:768
	global_load_dword v84, v[34:35], off offset:1024
	global_load_dword v85, v[34:35], off offset:1280
	global_load_dword v86, v[34:35], off offset:1536
	global_load_dword v87, v[34:35], off offset:1792
	global_load_dword v88, v[34:35], off offset:2048
	global_load_dword v89, v[34:35], off offset:2304
	global_load_dword v90, v[34:35], off offset:2560
	global_load_dword v91, v[34:35], off offset:2816
	global_load_dword v92, v[34:35], off offset:3072
	global_load_dword v93, v[34:35], off offset:3328
	global_load_dword v94, v[34:35], off offset:3584
	global_load_dword v95, v[34:35], off offset:3840
	s_add_u32 s2, s2, 0x1000
	s_addc_u32 s3, s3, 0
	v_add_u32_e32 v14, 64, v14
	s_cmpk_eq_i32 s2, 0x4000
	s_waitcnt vmcnt(15) lgkmcnt(3)
	v_fmac_f32_e32 v13, v16, v80
	s_waitcnt vmcnt(14)
	v_fmac_f32_e32 v13, v17, v81
	s_waitcnt vmcnt(13)
	v_fmac_f32_e32 v13, v18, v82
	s_waitcnt vmcnt(12)
	v_fmac_f32_e32 v13, v19, v83
	s_waitcnt vmcnt(11) lgkmcnt(2)
	v_fmac_f32_e32 v13, v20, v84
	s_waitcnt vmcnt(10)
	v_fmac_f32_e32 v13, v21, v85
	s_waitcnt vmcnt(9)
	v_fmac_f32_e32 v13, v22, v86
	s_waitcnt vmcnt(8)
	v_fmac_f32_e32 v13, v23, v87
	s_waitcnt vmcnt(7) lgkmcnt(1)
	v_fmac_f32_e32 v13, v24, v88
	s_waitcnt vmcnt(6)
	v_fmac_f32_e32 v13, v25, v89
	s_waitcnt vmcnt(5)
	v_fmac_f32_e32 v13, v26, v90
	s_waitcnt vmcnt(4)
	v_fmac_f32_e32 v13, v27, v91
	s_waitcnt vmcnt(3) lgkmcnt(0)
	v_fmac_f32_e32 v13, v28, v92
	s_waitcnt vmcnt(2)
	v_fmac_f32_e32 v13, v29, v93
	s_waitcnt vmcnt(1)
	v_fmac_f32_e32 v13, v30, v94
	s_waitcnt vmcnt(0)
	v_fmac_f32_e32 v13, v31, v95
	s_cbranch_scc0 .LBB0_160
	v_mul_f32_e32 v13, v7, v13
	v_and_b32_e32 v14, 0x7fffffff, v13
	v_cmp_nlt_f32_e64 s[2:3], |v13|, s24
	s_and_saveexec_b64 s[6:7], s[2:3]
	s_xor_b64 s[2:3], exec, s[6:7]
	s_cbranch_execz .LBB0_163
	v_lshrrev_b32_e32 v15, 23, v14
	v_add_u32_e32 v15, 0xffffff88, v15
	v_cmp_lt_u32_e32 vcc, 63, v15
	s_nop 1
	v_cndmask_b32_e32 v16, 0, v203, vcc
	v_add_u32_e32 v15, v16, v15
	v_cmp_lt_u32_e64 s[6:7], 31, v15
	s_nop 1
	v_cndmask_b32_e64 v16, 0, v204, s[6:7]
	v_add_u32_e32 v15, v16, v15
	v_cmp_lt_u32_e64 s[8:9], 31, v15
	s_nop 1
	v_cndmask_b32_e64 v16, 0, v204, s[8:9]
	v_add_u32_e32 v15, v16, v15
	v_and_b32_e32 v16, 0x7fffff, v14
	v_or_b32_e32 v28, 0x800000, v16
	v_mad_u64_u32 v[16:17], s[10:11], v28, s25, 0
	v_mov_b32_e32 v176, v17
	v_mad_u64_u32 v[18:19], s[10:11], v28, s26, v[176:177]
	v_mov_b32_e32 v176, v19
	v_mad_u64_u32 v[20:21], s[10:11], v28, s27, v[176:177]
	v_mov_b32_e32 v176, v21
	v_mad_u64_u32 v[22:23], s[10:11], v28, s34, v[176:177]
	v_mov_b32_e32 v176, v23
	v_mad_u64_u32 v[24:25], s[10:11], v28, s35, v[176:177]
	v_mov_b32_e32 v176, v25
	v_mad_u64_u32 v[26:27], s[10:11], v28, s36, v[176:177]
	v_mov_b32_e32 v176, v27
	v_mad_u64_u32 v[28:29], s[10:11], v28, s37, v[176:177]
	v_cndmask_b32_e32 v17, v26, v22, vcc
	v_cndmask_b32_e32 v19, v28, v24, vcc
	v_cndmask_b32_e32 v23, v29, v26, vcc
	v_cndmask_b32_e64 v21, v19, v17, s[6:7]
	v_cndmask_b32_e64 v19, v23, v19, s[6:7]
	v_cndmask_b32_e32 v23, v24, v20, vcc
	v_cndmask_b32_e64 v17, v17, v23, s[6:7]
	v_cndmask_b32_e64 v19, v19, v21, s[8:9]
	v_cndmask_b32_e64 v21, v21, v17, s[8:9]
	v_sub_u32_e32 v24, 32, v15
	v_alignbit_b32 v25, v19, v21, v24
	v_cmp_eq_u32_e64 s[10:11], 0, v15
	v_cndmask_b32_e32 v18, v22, v18, vcc
	v_cndmask_b32_e32 v16, v20, v16, vcc
	v_cndmask_b32_e64 v15, v25, v19, s[10:11]
	v_cndmask_b32_e64 v19, v23, v18, s[6:7]
	v_cndmask_b32_e64 v17, v17, v19, s[8:9]
	v_alignbit_b32 v22, v21, v17, v24
	v_cndmask_b32_e64 v21, v22, v21, s[10:11]
	v_bfe_u32 v25, v15, 29, 1
	v_cndmask_b32_e64 v16, v18, v16, s[6:7]
	v_alignbit_b32 v22, v15, v21, 30
	v_sub_u32_e32 v26, 0, v25
	v_cndmask_b32_e64 v16, v19, v16, s[8:9]
	v_xor_b32_e32 v22, v22, v26
	v_alignbit_b32 v18, v17, v16, v24
	v_cndmask_b32_e64 v17, v18, v17, s[10:11]
	v_ffbh_u32_e32 v19, v22
	v_alignbit_b32 v18, v21, v17, 30
	v_min_u32_e32 v19, 32, v19
	v_alignbit_b32 v16, v17, v16, 30
	v_xor_b32_e32 v18, v18, v26
	v_sub_u32_e32 v20, 31, v19
	v_xor_b32_e32 v16, v16, v26
	v_alignbit_b32 v21, v22, v18, v20
	v_alignbit_b32 v16, v18, v16, v20
	v_alignbit_b32 v17, v21, v16, 9
	v_ffbh_u32_e32 v18, v17
	v_min_u32_e32 v18, 32, v18
	v_lshrrev_b32_e32 v23, 29, v15
	v_not_b32_e32 v20, v18
	v_alignbit_b32 v16, v17, v16, v20
	v_lshlrev_b32_e32 v17, 31, v23
	v_or_b32_e32 v20, 0x33000000, v17
	v_add_lshl_u32 v18, v18, v19, 23
	v_lshrrev_b32_e32 v16, 9, v16
	v_sub_u32_e32 v18, v20, v18
	v_or_b32_e32 v17, 0.5, v17
	v_lshlrev_b32_e32 v19, 23, v19
	v_or_b32_e32 v16, v18, v16
	v_lshrrev_b32_e32 v18, 9, v21
	v_sub_u32_e32 v17, v17, v19
	v_or_b32_e32 v17, v18, v17
	v_mul_f32_e32 v18, 0x3fc90fda, v17
	v_fma_f32 v19, v17, s38, -v18
	v_fmac_f32_e32 v19, 0x33a22168, v17
	v_fmac_f32_e32 v19, 0x3fc90fda, v16
	v_lshrrev_b32_e32 v15, 30, v15
	v_add_f32_e32 v16, v18, v19
	v_add_u32_e32 v15, v25, v15

; __device__ __forceinline__ void prep_filter_item(const Params& p, int l, int it, char* smem, int wvi) {
;     ...
;     const float* W = p.fw3 + (size_t)l * 64 * 64; const float bb = p.fb3[l * 64 + u];
; #pragma unroll 1
;     for (int q = 0; q < 4; ++q) {
;       const int ps = pg * 4 + q; float a = bb;
;       for (int k = 0; k < 64; ++k) a += sH2[ps * 64 + k] * W[k * 64 + u];
;       sH3[ps * 64 + u] = sinf(fr * a);
;     }
.LBB0_168:
	v_lshl_add_u64 v[10:11], v[0:1], 0, s[2:3]
	v_add_co_u32_e32 v10, vcc, 0x4000, v10
	s_add_u32 s2, s2, 0x1000
	s_nop 0
	v_addc_co_u32_e32 v11, vcc, 0, v11, vcc
	global_load_dword v80, v[10:11], off
	global_load_dword v81, v[10:11], off offset:256
	global_load_dword v82, v[10:11], off offset:512
	global_load_dword v83, v[10:11], off offset:768
	global_load_dword v84, v[10:11], off offset:1024
	global_load_dword v85, v[10:11], off offset:1280
	global_load_dword v86, v[10:11], off offset:1536
	global_load_dword v87, v[10:11], off offset:1792
	global_load_dword v88, v[10:11], off offset:2048
	global_load_dword v89, v[10:11], off offset:2304
	global_load_dword v90, v[10:11], off offset:2560
	global_load_dword v91, v[10:11], off offset:2816
	global_load_dword v92, v[10:11], off offset:3072
	global_load_dword v93, v[10:11], off offset:3328
	global_load_dword v94, v[10:11], off offset:3584
	global_load_dword v95, v[10:11], off offset:3840
	ds_read_b128 v[10:13], v3
	ds_read_b128 v[14:17], v3 offset:16
	ds_read_b128 v[18:21], v3 offset:32
	ds_read_b128 v[22:25], v3 offset:48
	s_addc_u32 s3, s3, 0
	v_add_u32_e32 v3, 64, v3
	s_cmpk_eq_i32 s2, 0x4000
	s_waitcnt vmcnt(15) lgkmcnt(3)
	v_fmac_f32_e32 v2, v10, v80
	s_waitcnt vmcnt(14)
	v_fmac_f32_e32 v2, v11, v81
	s_waitcnt vmcnt(13)
	v_fmac_f32_e32 v2, v12, v82
	s_waitcnt vmcnt(12)
	v_fmac_f32_e32 v2, v13, v83
	s_waitcnt vmcnt(11) lgkmcnt(2)
	v_fmac_f32_e32 v2, v14, v84
	s_waitcnt vmcnt(10)
	v_fmac_f32_e32 v2, v15, v85
	s_waitcnt vmcnt(9)
	v_fmac_f32_e32 v2, v16, v86
	s_waitcnt vmcnt(8)
	v_fmac_f32_e32 v2, v17, v87
	s_waitcnt vmcnt(7) lgkmcnt(1)
	v_fmac_f32_e32 v2, v18, v88
	s_waitcnt vmcnt(6)
	v_fmac_f32_e32 v2, v19, v89
	s_waitcnt vmcnt(5)
	v_fmac_f32_e32 v2, v20, v90
	s_waitcnt vmcnt(4)
	v_fmac_f32_e32 v2, v21, v91
	s_waitcnt vmcnt(3) lgkmcnt(0)
	v_fmac_f32_e32 v2, v22, v92
	s_waitcnt vmcnt(2)
	v_fmac_f32_e32 v2, v23, v93
	s_waitcnt vmcnt(1)
	v_fmac_f32_e32 v2, v24, v94
	s_waitcnt vmcnt(0)
	v_fmac_f32_e32 v2, v25, v95
	s_cbranch_scc0 .LBB0_168
	v_mul_f32_e32 v2, v7, v2
	v_and_b32_e32 v3, 0x7fffffff, v2
	v_cmp_nlt_f32_e64 s[2:3], |v2|, s24
	s_and_saveexec_b64 s[6:7], s[2:3]
	s_xor_b64 s[2:3], exec, s[6:7]
	s_cbranch_execz .LBB0_171
	v_lshrrev_b32_e32 v10, 23, v3
	v_add_u32_e32 v10, 0xffffff88, v10
	v_cmp_lt_u32_e32 vcc, 63, v10
	s_nop 1
	v_cndmask_b32_e32 v11, 0, v203, vcc
	v_add_u32_e32 v10, v11, v10
	v_cmp_lt_u32_e64 s[6:7], 31, v10
	s_nop 1
	v_cndmask_b32_e64 v11, 0, v204, s[6:7]
	v_add_u32_e32 v10, v11, v10
	v_cmp_lt_u32_e64 s[8:9], 31, v10
	s_nop 1
	v_cndmask_b32_e64 v11, 0, v204, s[8:9]
	v_add_u32_e32 v24, v11, v10
	v_and_b32_e32 v10, 0x7fffff, v3
	v_or_b32_e32 v22, 0x800000, v10
	v_mad_u64_u32 v[10:11], s[10:11], v22, s25, 0
	v_mov_b32_e32 v176, v11
	v_mad_u64_u32 v[12:13], s[10:11], v22, s26, v[176:177]
	v_mov_b32_e32 v176, v13
	v_mad_u64_u32 v[14:15], s[10:11], v22, s27, v[176:177]
	v_mov_b32_e32 v176, v15
	v_mad_u64_u32 v[16:17], s[10:11], v22, s34, v[176:177]
	v_mov_b32_e32 v176, v17
	v_mad_u64_u32 v[18:19], s[10:11], v22, s35, v[176:177]
	v_mov_b32_e32 v176, v19
	v_mad_u64_u32 v[20:21], s[10:11], v22, s36, v[176:177]
	v_mov_b32_e32 v176, v21
	v_mad_u64_u32 v[22:23], s[10:11], v22, s37, v[176:177]
	v_cndmask_b32_e32 v11, v20, v16, vcc
	v_cndmask_b32_e32 v13, v22, v18, vcc
	v_cndmask_b32_e32 v17, v23, v20, vcc
	v_cndmask_b32_e64 v15, v13, v11, s[6:7]
	v_cndmask_b32_e64 v13, v17, v13, s[6:7]
	v_cndmask_b32_e32 v17, v18, v14, vcc
	v_cndmask_b32_e64 v11, v11, v17, s[6:7]
	v_cndmask_b32_e32 v12, v16, v12, vcc
	v_cndmask_b32_e64 v13, v13, v15, s[8:9]
	v_cndmask_b32_e64 v15, v15, v11, s[8:9]
	v_sub_u32_e32 v18, 32, v24
	v_cndmask_b32_e64 v16, v17, v12, s[6:7]
	v_alignbit_b32 v19, v13, v15, v18
	v_cmp_eq_u32_e64 s[10:11], 0, v24
	v_cndmask_b32_e64 v11, v11, v16, s[8:9]
	v_alignbit_b32 v17, v15, v11, v18
	v_cndmask_b32_e64 v13, v19, v13, s[10:11]
	v_cndmask_b32_e32 v10, v14, v10, vcc
	v_cndmask_b32_e64 v15, v17, v15, s[10:11]
	v_bfe_u32 v20, v13, 29, 1
	v_cndmask_b32_e64 v10, v12, v10, s[6:7]
	v_alignbit_b32 v17, v13, v15, 30
	v_sub_u32_e32 v21, 0, v20
	v_cndmask_b32_e64 v10, v16, v10, s[8:9]
	v_xor_b32_e32 v17, v17, v21
	v_alignbit_b32 v12, v11, v10, v18
	v_cndmask_b32_e64 v11, v12, v11, s[10:11]
	v_ffbh_u32_e32 v14, v17
	v_alignbit_b32 v12, v15, v11, 30
	v_min_u32_e32 v14, 32, v14
	v_alignbit_b32 v10, v11, v10, 30
	v_xor_b32_e32 v12, v12, v21
	v_sub_u32_e32 v15, 31, v14
	v_xor_b32_e32 v10, v10, v21
	v_alignbit_b32 v16, v17, v12, v15
	v_alignbit_b32 v10, v12, v10, v15
	v_alignbit_b32 v11, v16, v10, 9
	v_ffbh_u32_e32 v12, v11
	v_min_u32_e32 v12, 32, v12
	v_lshrrev_b32_e32 v19, 29, v13
	v_not_b32_e32 v15, v12
	v_alignbit_b32 v10, v11, v10, v15
	v_lshlrev_b32_e32 v11, 31, v19
	v_or_b32_e32 v15, 0x33000000, v11
	v_add_lshl_u32 v12, v12, v14, 23
	v_lshrrev_b32_e32 v10, 9, v10
	v_sub_u32_e32 v12, v15, v12
	v_or_b32_e32 v11, 0.5, v11
	v_lshlrev_b32_e32 v14, 23, v14
	v_or_b32_e32 v10, v12, v10
	v_lshrrev_b32_e32 v12, 9, v16
	v_sub_u32_e32 v11, v11, v14
	v_or_b32_e32 v11, v12, v11
	v_mul_f32_e32 v12, 0x3fc90fda, v11
	v_fma_f32 v14, v11, s38, -v12
	v_fmac_f32_e32 v14, 0x33a22168, v11
	v_fmac_f32_e32 v14, 0x3fc90fda, v10
	v_lshrrev_b32_e32 v10, 30, v13
	v_add_f32_e32 v11, v12, v14
	v_add_u32_e32 v10, v20, v10

; __device__ __forceinline__ void prep_filter_item(const Params& p, int l, int it, char* smem, int wvi) {
;     ...
;   for (int cc = 0; cc < 4; ++cc) {
;     const int col = tid + 256 * cc;
;     const int o = col >> 9, dr = (col >> 8) & 1, ch = col & 255;
;     const float dl = fabsf(a0 + (float)ch * ((a1 - a0) / 255.f));
;     for (int half = 0; half < 2; ++half) {
;       float acc[8];
; #pragma unroll
;       for (int q = 0; q < 8; ++q) acc[q] = 0.f;
;       for (int k = 0; k < 64; ++k) {
;         const float wv = W4[k * 1024 + col];
; #pragma unroll
;         for (int q = 0; q < 8; ++q) acc[q] += sH3[(half * 8 + q) * 64 + k] * wv;
;       }
; #pragma unroll
;       for (int q = 0; q < 8; ++q) {
;         const int i = pos0 + half * 8 + q;
;         const float t = (float)i * inv_lm1;
;         const float v = acc[q] * expf(-t * dl);
;         float* kb = (L == SEQ) ? p.kfl + (size_t)(o * 256 + ch) * 8192 : p.kfc + (size_t)(o * 256 + ch) * 512;
;         const int mid = (L == SEQ) ? 4096 : 256;
;         const int idx = (dr == 0) ? mid + i : ((i >= 1) ? mid - i : 0);
;         kb[idx] = v;
;       }
.LBB0_175:
	global_load_dword v40, v[36:37], off
	v_add_u32_e32 v84, s96, v33
	v_add_u32_e32 v86, 0x400, v84
	v_ashrrev_i32_e32 v87, 31, v86
	v_lshl_add_u64 v[86:87], v[86:87], 2, s[16:17]
	global_load_dword v90, v[86:87], off
	v_add_u32_e32 v88, 0x800, v84
	v_ashrrev_i32_e32 v89, 31, v88
	v_lshl_add_u64 v[88:89], v[88:89], 2, s[16:17]
	global_load_dword v92, v[88:89], off
	v_add_u32_e32 v96, 0xc00, v84
	v_ashrrev_i32_e32 v97, 31, v96
	v_lshl_add_u64 v[96:97], v[96:97], 2, s[16:17]
	global_load_dword v94, v[96:97], off
	v_mov_b32_e32 v28, s97
	ds_read_b128 v[0:3], v28
	ds_read_b128 v[4:7], v28 offset:256
	s_add_i32 s97, s97, 16
	v_lshl_add_u64 v[36:37], v[36:37], 0, s[84:85]
	s_waitcnt lgkmcnt(1)
	v_mov_b32_e32 v10, v0
	s_waitcnt lgkmcnt(0)
	v_mov_b32_e32 v11, v4
	v_mov_b32_e32 v4, v1
	s_waitcnt vmcnt(3)
	v_pk_fma_f32 v[60:61], v[40:41], v[10:11], v[8:9] op_sel_hi:[0,1,1]
	ds_read_b128 v[8:11], v28 offset:512
	ds_read_b128 v[12:15], v28 offset:768
	s_waitcnt lgkmcnt(1)
	v_mov_b32_e32 v18, v8
	s_waitcnt lgkmcnt(0)
	v_mov_b32_e32 v19, v12
	v_pk_fma_f32 v[62:63], v[40:41], v[18:19], v[16:17] op_sel_hi:[0,1,1]
	ds_read_b128 v[16:19], v28 offset:1024
	ds_read_b128 v[20:23], v28 offset:1280
	v_mov_b32_e32 v12, v9
	s_waitcnt lgkmcnt(1)
	v_mov_b32_e32 v26, v16
	s_waitcnt lgkmcnt(0)
	v_mov_b32_e32 v27, v20
	v_pk_fma_f32 v[64:65], v[40:41], v[26:27], v[24:25] op_sel_hi:[0,1,1]
	ds_read_b128 v[24:27], v28 offset:1536
	ds_read_b128 v[28:31], v28 offset:1792
	v_mov_b32_e32 v20, v17
	s_waitcnt lgkmcnt(1)
	v_mov_b32_e32 v66, v24
	s_waitcnt lgkmcnt(0)
	v_mov_b32_e32 v67, v28
	v_pk_fma_f32 v[38:39], v[40:41], v[66:67], v[38:39] op_sel_hi:[0,1,1]
	v_mov_b32_e32 v28, v25
	s_addk_i32 s96, 0x1000
	s_cmp_eq_u32 s96, 0x10000
	s_waitcnt vmcnt(2)
	v_pk_fma_f32 v[4:5], v[90:91], v[4:5], v[60:61] op_sel_hi:[0,1,1]
	v_pk_fma_f32 v[8:9], v[90:91], v[12:13], v[62:63] op_sel_hi:[0,1,1]
	v_pk_fma_f32 v[12:13], v[90:91], v[20:21], v[64:65] op_sel_hi:[0,1,1]
	v_mov_b32_e32 v20, v2
	v_mov_b32_e32 v21, v6
	s_waitcnt vmcnt(1)
	v_pk_fma_f32 v[4:5], v[92:93], v[20:21], v[4:5] op_sel_hi:[0,1,1]
	v_mov_b32_e32 v20, v10
	v_mov_b32_e32 v21, v14
	v_pk_fma_f32 v[20:21], v[92:93], v[20:21], v[8:9] op_sel_hi:[0,1,1]
	v_mov_b32_e32 v8, v18
	v_mov_b32_e32 v9, v22
	v_pk_fma_f32 v[0:1], v[90:91], v[28:29], v[38:39] op_sel_hi:[0,1,1]
	v_pk_fma_f32 v[12:13], v[92:93], v[8:9], v[12:13] op_sel_hi:[0,1,1]
	v_mov_b32_e32 v8, v26
	v_mov_b32_e32 v9, v30
	v_pk_fma_f32 v[0:1], v[92:93], v[8:9], v[0:1] op_sel_hi:[0,1,1]
	v_mov_b32_e32 v6, v3
	v_mov_b32_e32 v14, v11
	v_mov_b32_e32 v22, v19
	v_mov_b32_e32 v30, v27
	s_waitcnt vmcnt(0)
	v_pk_fma_f32 v[8:9], v[94:95], v[6:7], v[4:5] op_sel_hi:[0,1,1]
	v_pk_fma_f32 v[16:17], v[94:95], v[14:15], v[20:21] op_sel_hi:[0,1,1]
	v_pk_fma_f32 v[24:25], v[94:95], v[22:23], v[12:13] op_sel_hi:[0,1,1]
	v_pk_fma_f32 v[38:39], v[94:95], v[30:31], v[0:1] op_sel_hi:[0,1,1]
	s_cbranch_scc0 .LBB0_175
	v_lshl_add_u32 v2, s6, 8, v32
	v_ashrrev_i32_e32 v0, 1, v2
	s_movk_i32 s13, 0xff00
	v_and_or_b32 v0, v0, s13, v42
	v_ashrrev_i32_e32 v1, 31, v0
	v_readlane_b32 s36, v245, 51
	v_and_b32_e32 v4, 0x100, v2
	v_lshlrev_b64 v[2:3], 11, v[0:1]
	v_lshlrev_b64 v[0:1], 15, v[0:1]
	v_readlane_b32 s38, v245, 53
	v_readlane_b32 s39, v245, 54
	v_readlane_b32 s40, v245, 55
	v_readlane_b32 s41, v245, 56
	v_lshl_add_u64 v[0:1], s[38:39], 0, v[0:1]
	v_cmp_eq_u32_e32 vcc, 0, v4
	v_lshl_add_u64 v[2:3], s[40:41], 0, v[2:3]
	v_cndmask_b32_e64 v37, v3, v1, s[44:45]
	v_cndmask_b32_e64 v36, v2, v0, s[44:45]
	v_mov_b32_e32 v0, s3
	v_mov_b32_e32 v1, s2
	v_cndmask_b32_e32 v0, v0, v1, vcc
	v_ashrrev_i32_e32 v1, 31, v0
	v_mul_f32_e32 v4, v43, v8
	v_lshl_add_u64 v[0:1], v[0:1], 2, v[36:37]
	global_store_dword v[0:1], v4, off
	v_mov_b32_e32 v0, s20
	v_mov_b32_e32 v1, s7
	v_cndmask_b32_e32 v0, v0, v1, vcc
	v_ashrrev_i32_e32 v1, 31, v0
	v_mul_f32_e32 v2, v44, v9
	v_lshl_add_u64 v[0:1], v[0:1], 2, v[36:37]
	global_store_dword v[0:1], v2, off
	v_mov_b32_e32 v0, s27
	v_mov_b32_e32 v1, s8
	v_cndmask_b32_e32 v0, v0, v1, vcc
	v_ashrrev_i32_e32 v1, 31, v0
	v_mul_f32_e32 v2, v45, v16
	v_lshl_add_u64 v[0:1], v[0:1], 2, v[36:37]
	global_store_dword v[0:1], v2, off
	v_mov_b32_e32 v0, s28
	v_mov_b32_e32 v1, s9
	v_cndmask_b32_e32 v0, v0, v1, vcc
	v_ashrrev_i32_e32 v1, 31, v0
	v_mul_f32_e32 v2, v46, v17
	v_lshl_add_u64 v[0:1], v[0:1], 2, v[36:37]
	global_store_dword v[0:1], v2, off
	v_mov_b32_e32 v0, s29
	v_mov_b32_e32 v1, s10
	v_cndmask_b32_e32 v0, v0, v1, vcc
	v_ashrrev_i32_e32 v1, 31, v0
	v_mul_f32_e32 v2, v47, v24
	v_lshl_add_u64 v[0:1], v[0:1], 2, v[36:37]
	global_store_dword v[0:1], v2, off
	v_mov_b32_e32 v0, s30
	v_mov_b32_e32 v1, s11
	v_cndmask_b32_e32 v0, v0, v1, vcc
	v_ashrrev_i32_e32 v1, 31, v0
	v_mul_f32_e32 v2, v48, v25
	v_lshl_add_u64 v[0:1], v[0:1], 2, v[36:37]
	global_store_dword v[0:1], v2, off
	v_mov_b32_e32 v0, s31
	v_mov_b32_e32 v1, s12
	v_cndmask_b32_e32 v0, v0, v1, vcc
	v_ashrrev_i32_e32 v1, 31, v0
	v_mul_f32_e32 v2, v49, v38
	v_lshl_add_u64 v[0:1], v[0:1], 2, v[36:37]
	global_store_dword v[0:1], v2, off
	v_mov_b32_e32 v0, s88
	v_mov_b32_e32 v1, s91
	v_cndmask_b32_e32 v0, v0, v1, vcc
	v_ashrrev_i32_e32 v1, 31, v0
	v_mov_b32_e32 v40, 0
	s_mov_b32 s96, 0
	v_mul_f32_e32 v2, v50, v39
	v_lshl_add_u64 v[0:1], v[0:1], 2, v[36:37]
	v_mov_b64_e32 v[38:39], v[34:35]
	v_readlane_b32 s97, v246, 37
	v_mov_b32_e32 v41, v40
	v_mov_b32_e32 v8, v40
	v_mov_b32_e32 v9, v40
	v_mov_b32_e32 v16, v40
	v_mov_b32_e32 v17, v40
	v_mov_b32_e32 v24, v40
	v_mov_b32_e32 v25, v40
	v_readlane_b32 s37, v245, 52
	v_readlane_b32 s42, v245, 57
	v_readlane_b32 s43, v245, 58
	global_store_dword v[0:1], v2, off
; __device__ __forceinline__ void prep_filter_item(const Params& p, int l, int it, char* smem, int wvi) {
;     ...
;   for (int cc = 0; cc < 4; ++cc) {
;     const int col = tid + 256 * cc;
;     const int o = col >> 9, dr = (col >> 8) & 1, ch = col & 255;
;     const float dl = fabsf(a0 + (float)ch * ((a1 - a0) / 255.f));
;     for (int half = 0; half < 2; ++half) {
;       float acc[8];
; #pragma unroll
;       for (int q = 0; q < 8; ++q) acc[q] = 0.f;
;       for (int k = 0; k < 64; ++k) {
;         const float wv = W4[k * 1024 + col];
; #pragma unroll
;         for (int q = 0; q < 8; ++q) acc[q] += sH3[(half * 8 + q) * 64 + k] * wv;
;       }
; #pragma unroll
;       for (int q = 0; q < 8; ++q) {
;         const int i = pos0 + half * 8 + q;
;         const float t = (float)i * inv_lm1;
;         const float v = acc[q] * expf(-t * dl);
;         float* kb = (L == SEQ) ? p.kfl + (size_t)(o * 256 + ch) * 8192 : p.kfc + (size_t)(o * 256 + ch) * 512;
;         const int mid = (L == SEQ) ? 4096 : 256;
;         const int idx = (dr == 0) ? mid + i : ((i >= 1) ? mid - i : 0);
;         kb[idx] = v;
;       }
.LBB0_177:
	global_load_dword v60, v[38:39], off
	v_add_u32_e32 v84, s96, v33
	v_add_u32_e32 v86, 0x400, v84
	v_ashrrev_i32_e32 v87, 31, v86
	v_lshl_add_u64 v[86:87], v[86:87], 2, s[16:17]
	global_load_dword v90, v[86:87], off
	v_add_u32_e32 v88, 0x800, v84
	v_ashrrev_i32_e32 v89, 31, v88
	v_lshl_add_u64 v[88:89], v[88:89], 2, s[16:17]
	global_load_dword v92, v[88:89], off
	v_add_u32_e32 v96, 0xc00, v84
	v_ashrrev_i32_e32 v97, 31, v96
	v_lshl_add_u64 v[96:97], v[96:97], 2, s[16:17]
	global_load_dword v94, v[96:97], off
	v_mov_b32_e32 v28, s97
	ds_read_b128 v[0:3], v28
	ds_read_b128 v[4:7], v28 offset:256
	s_add_i32 s97, s97, 16
	v_lshl_add_u64 v[38:39], v[38:39], 0, s[84:85]
	s_waitcnt lgkmcnt(1)
	v_mov_b32_e32 v10, v0
	s_waitcnt lgkmcnt(0)
	v_mov_b32_e32 v11, v4
	v_mov_b32_e32 v4, v1
	s_waitcnt vmcnt(3)
	v_pk_fma_f32 v[62:63], v[60:61], v[10:11], v[8:9] op_sel_hi:[0,1,1]
	ds_read_b128 v[8:11], v28 offset:512
	ds_read_b128 v[12:15], v28 offset:768
	s_waitcnt lgkmcnt(1)
	v_mov_b32_e32 v18, v8
	s_waitcnt lgkmcnt(0)
	v_mov_b32_e32 v19, v12
	v_pk_fma_f32 v[64:65], v[60:61], v[18:19], v[16:17] op_sel_hi:[0,1,1]
	ds_read_b128 v[16:19], v28 offset:1024
	ds_read_b128 v[20:23], v28 offset:1280
	v_mov_b32_e32 v12, v9
	s_waitcnt lgkmcnt(1)
	v_mov_b32_e32 v26, v16
	s_waitcnt lgkmcnt(0)
	v_mov_b32_e32 v27, v20
	v_pk_fma_f32 v[66:67], v[60:61], v[26:27], v[24:25] op_sel_hi:[0,1,1]
	ds_read_b128 v[24:27], v28 offset:1536
	ds_read_b128 v[28:31], v28 offset:1792
	v_mov_b32_e32 v20, v17
	s_waitcnt lgkmcnt(1)
	v_mov_b32_e32 v68, v24
	s_waitcnt lgkmcnt(0)
	v_mov_b32_e32 v69, v28
	v_pk_fma_f32 v[40:41], v[60:61], v[68:69], v[40:41] op_sel_hi:[0,1,1]
	v_mov_b32_e32 v28, v25
	s_addk_i32 s96, 0x1000
	s_cmp_lg_u32 s96, 0x10000
	s_waitcnt vmcnt(2)
	v_pk_fma_f32 v[4:5], v[90:91], v[4:5], v[62:63] op_sel_hi:[0,1,1]
	v_pk_fma_f32 v[8:9], v[90:91], v[12:13], v[64:65] op_sel_hi:[0,1,1]
	v_pk_fma_f32 v[12:13], v[90:91], v[20:21], v[66:67] op_sel_hi:[0,1,1]
	v_mov_b32_e32 v20, v2
	v_mov_b32_e32 v21, v6
	s_waitcnt vmcnt(1)
	v_pk_fma_f32 v[4:5], v[92:93], v[20:21], v[4:5] op_sel_hi:[0,1,1]
	v_mov_b32_e32 v20, v10
	v_mov_b32_e32 v21, v14
	v_pk_fma_f32 v[20:21], v[92:93], v[20:21], v[8:9] op_sel_hi:[0,1,1]
	v_mov_b32_e32 v8, v18
	v_mov_b32_e32 v9, v22
	v_pk_fma_f32 v[0:1], v[90:91], v[28:29], v[40:41] op_sel_hi:[0,1,1]
	v_pk_fma_f32 v[12:13], v[92:93], v[8:9], v[12:13] op_sel_hi:[0,1,1]
	v_mov_b32_e32 v8, v26
	v_mov_b32_e32 v9, v30
	v_pk_fma_f32 v[0:1], v[92:93], v[8:9], v[0:1] op_sel_hi:[0,1,1]
	v_mov_b32_e32 v6, v3
	v_mov_b32_e32 v14, v11
	v_mov_b32_e32 v22, v19
	v_mov_b32_e32 v30, v27
	s_waitcnt vmcnt(0)
	v_pk_fma_f32 v[8:9], v[94:95], v[6:7], v[4:5] op_sel_hi:[0,1,1]
	v_pk_fma_f32 v[16:17], v[94:95], v[14:15], v[20:21] op_sel_hi:[0,1,1]
	v_pk_fma_f32 v[24:25], v[94:95], v[22:23], v[12:13] op_sel_hi:[0,1,1]
	v_pk_fma_f32 v[40:41], v[94:95], v[30:31], v[0:1] op_sel_hi:[0,1,1]
	s_cbranch_scc1 .LBB0_177
	v_mov_b32_e32 v0, s89
	v_mov_b32_e32 v1, s14
	v_cndmask_b32_e32 v0, v0, v1, vcc
	v_ashrrev_i32_e32 v1, 31, v0
	v_mul_f32_e32 v2, v51, v8
	v_lshl_add_u64 v[0:1], v[0:1], 2, v[36:37]
	global_store_dword v[0:1], v2, off
	v_mov_b32_e32 v0, s92
	v_mov_b32_e32 v1, s95
	v_cndmask_b32_e32 v0, v0, v1, vcc
	v_ashrrev_i32_e32 v1, 31, v0
	v_mul_f32_e32 v2, v52, v9
	v_lshl_add_u64 v[0:1], v[0:1], 2, v[36:37]
	global_store_dword v[0:1], v2, off
	v_mov_b32_e32 v0, s93
	v_mov_b32_e32 v1, s21
	v_cndmask_b32_e32 v0, v0, v1, vcc
	v_ashrrev_i32_e32 v1, 31, v0
	v_mul_f32_e32 v2, v53, v16
	v_lshl_add_u64 v[0:1], v[0:1], 2, v[36:37]
	global_store_dword v[0:1], v2, off
	v_mov_b32_e32 v0, s53
	v_mov_b32_e32 v1, s22
	v_cndmask_b32_e32 v0, v0, v1, vcc
	v_ashrrev_i32_e32 v1, 31, v0
	v_mul_f32_e32 v2, v54, v17
	v_lshl_add_u64 v[0:1], v[0:1], 2, v[36:37]
	global_store_dword v[0:1], v2, off
	v_mov_b32_e32 v0, s1
	v_mov_b32_e32 v1, s23
	v_cndmask_b32_e32 v0, v0, v1, vcc
	v_ashrrev_i32_e32 v1, 31, v0
	v_mul_f32_e32 v2, v55, v24
	v_lshl_add_u64 v[0:1], v[0:1], 2, v[36:37]
	global_store_dword v[0:1], v2, off
	v_mov_b32_e32 v0, s0
	v_mov_b32_e32 v1, s24
	v_cndmask_b32_e32 v0, v0, v1, vcc
	v_ashrrev_i32_e32 v1, 31, v0
	v_mul_f32_e32 v2, v56, v25
	v_lshl_add_u64 v[0:1], v[0:1], 2, v[36:37]
	global_store_dword v[0:1], v2, off
	v_mov_b32_e32 v0, s63
	v_mov_b32_e32 v1, s25
	v_cndmask_b32_e32 v0, v0, v1, vcc
	v_ashrrev_i32_e32 v1, 31, v0
	v_mul_f32_e32 v2, v57, v40
	v_lshl_add_u64 v[0:1], v[0:1], 2, v[36:37]
	global_store_dword v[0:1], v2, off
	v_mov_b32_e32 v0, s67
	v_mov_b32_e32 v1, s26
	v_cndmask_b32_e32 v0, v0, v1, vcc
	v_ashrrev_i32_e32 v1, 31, v0
	s_add_i32 s6, s6, 1
	s_mov_b64 s[18:19], 0x400
	v_mul_f32_e32 v2, v58, v41
	v_lshl_add_u64 v[0:1], v[0:1], 2, v[36:37]
	v_add_u32_e32 v33, 0x100, v33
	s_cmp_lg_u32 s6, 4
	v_lshl_add_u64 v[34:35], v[34:35], 0, s[18:19]
	global_store_dword v[0:1], v2, off
	s_cbranch_scc1 .LBB0_174
	v_readlane_b32 s67, v244, 20
	v_readlane_b32 s94, v244, 13
	s_add_i32 s47, s47, s67
	v_readlane_b32 s90, v244, 11
	v_readlane_b32 s95, v244, 14
	v_readlane_b32 s96, v244, 34
	s_cmpk_lt_i32 s47, 0x110
	v_readlane_b32 s91, v244, 12
	v_readlane_b32 s97, v244, 35
	v_readlane_b32 s95, v244, 16
	v_readlane_b32 s63, v244, 19
	s_movk_i32 s53, 0x440
	s_cbranch_scc1 .LBB0_130

; __device__ __forceinline__ void hy_final_item(const Params& p, int l, int pi, char* smem, int wvi) {
;     ...
;   __syncthreads();
; #pragma unroll
;   for (int i = 0; i < 8; ++i) {
;     const int slot = tid + 256 * i, c = slot >> 3, part = slot & 7;
;     const u32x4 v = *reinterpret_cast<const u32x4*>(p.hyT + (size_t)c * TA + tok0 + part * 8);
;     unsigned* d = reinterpret_cast<unsigned*>(sZ + c * 66 + part * 8);
;     d[0] = v.x; d[1] = v.y; d[2] = v.z; d[3] = v.w;
;   }
;   __syncthreads();
.LBB0_384:
	s_lshl_b32 s20, s23, 6
	s_waitcnt vmcnt(1)
	v_mbcnt_lo_u32_b32 v0, -1, 0
	v_mbcnt_hi_u32_b32 v0, -1, v0
	s_ashr_i32 s21, s20, 31
	v_add_u32_e32 v0, s95, v0
	s_lshl_b64 s[0:1], s[20:21], 1
	s_add_u32 s0, s18, s0
	v_lshlrev_b32_e32 v1, 4, v0
	s_addc_u32 s1, s19, s1
	v_and_b32_e32 v176, 0x70, v1
	s_waitcnt vmcnt(0)
	v_lshl_add_u64 v[6:7], s[0:1], 0, v[176:177]
	v_ashrrev_i32_e32 v1, 3, v0
	s_mov_b32 s3, 0x22000
	v_mad_i64_i32 v[2:3], s[0:1], v1, s3, v[6:7]
	s_barrier
	v_add_u32_e32 v8, s52, v176
	s_movk_i32 s2, 0x84
	v_mad_u64_u32 v[10:11], s[0:1], v1, s2, v[8:9]
	v_and_b32_e32 v30, 63, v0
	s_mov_b64 s[0:1], 0x440000
	global_load_dwordx4 v[32:35], v[2:3], off
	v_lshl_add_u64 v[2:3], v[2:3], 0, s[0:1]
	global_load_dwordx4 v[36:39], v[2:3], off
	v_lshl_add_u64 v[2:3], v[2:3], 0, s[0:1]
	global_load_dwordx4 v[40:43], v[2:3], off
	v_lshl_add_u64 v[2:3], v[2:3], 0, s[0:1]
	global_load_dwordx4 v[44:47], v[2:3], off
	v_lshl_add_u64 v[2:3], v[2:3], 0, s[0:1]
	global_load_dwordx4 v[48:51], v[2:3], off
	v_lshl_add_u64 v[2:3], v[2:3], 0, s[0:1]
	global_load_dwordx4 v[52:55], v[2:3], off
	v_lshl_add_u64 v[2:3], v[2:3], 0, s[0:1]
	global_load_dwordx4 v[56:59], v[2:3], off
	v_lshl_add_u64 v[2:3], v[2:3], 0, s[0:1]
	global_load_dwordx4 v[60:63], v[2:3], off
	s_waitcnt vmcnt(7)
	ds_write2_b32 v10, v32, v33 offset1:1
	ds_write2_b32 v10, v34, v35 offset0:2 offset1:3
	s_waitcnt vmcnt(6)
	v_add_u32_e32 v11, 4224, v10
	ds_write2_b32 v11, v36, v37 offset1:1
	ds_write2_b32 v11, v38, v39 offset0:2 offset1:3
	s_waitcnt vmcnt(5)
	v_add_u32_e32 v11, 8448, v10
	ds_write2_b32 v11, v40, v41 offset1:1
	ds_write2_b32 v11, v42, v43 offset0:2 offset1:3
	s_waitcnt vmcnt(4)
	v_add_u32_e32 v11, 12672, v10
	ds_write2_b32 v11, v44, v45 offset1:1
	ds_write2_b32 v11, v46, v47 offset0:2 offset1:3
	s_waitcnt vmcnt(3)
	v_add_u32_e32 v11, 16896, v10
	ds_write2_b32 v11, v48, v49 offset1:1
	ds_write2_b32 v11, v50, v51 offset0:2 offset1:3
	s_waitcnt vmcnt(2)
	v_add_u32_e32 v11, 21120, v10
	ds_write2_b32 v11, v52, v53 offset1:1
	ds_write2_b32 v11, v54, v55 offset0:2 offset1:3
	s_waitcnt vmcnt(1)
	v_add_u32_e32 v11, 25344, v10
	ds_write2_b32 v11, v56, v57 offset1:1
	ds_write2_b32 v11, v58, v59 offset0:2 offset1:3
	s_waitcnt vmcnt(0)
	v_add_u32_e32 v11, 29568, v10
	ds_write2_b32 v11, v60, v61 offset1:1
	ds_write2_b32 v11, v62, v63 offset0:2 offset1:3
	s_movk_i32 s0, 0x2100
	v_or_b32_e32 v1, 63, v0
	s_mov_b64 s[2:3], 0
	v_lshrrev_b32_e32 v3, 6, v0
	v_mul_lo_u32 v3, v3, s0
	v_and_b32_e32 v2, 0xffffffc0, v0
	v_lshl_or_b32 v3, v30, 1, v3
	v_add_u32_e32 v2, -1, v2
	v_add_u32_e32 v4, s52, v3
	v_mov_b32_e32 v3, 0
	s_waitcnt lgkmcnt(0)
	s_barrier

; __device__ __forceinline__ u32x2 mk2(unsigned a, unsigned b) { return (u32x2){a, b}; }
; __device__ __forceinline__ float lo2f(unsigned u) { return __uint_as_float(u << 16); }
; __device__ __forceinline__ void shortconv_tokens(const Params& p, int l, int wvi) {
;     ...
;   const int per = (TA + nw - 1) / nw, gw = obid(wvi) * 4 + w;
;   const int r0 = gw * per, r1 = min(TA, r0 + per);
;   if (r0 >= r1) return;
;   const u32x2 z2 = mk2(0u, 0u);
;   u32x2 gcp = z2, hxp = z2, gcc, hxc, gbc, gcn = z2, hxn = z2, gbn = z2;
;   if (r0 > 0) { gcp = *reinterpret_cast<const u32x2*>(ps + (size_t)(r0 - 1) * 768 + 256 + ch); hxp = *reinterpret_cast<const u32x2*>(ps + (size_t)(r0 - 1) * 768 + 512 + ch); }
;   gbc = *reinterpret_cast<const u32x2*>(ps + (size_t)r0 * 768 + ch);
;   gcc = *reinterpret_cast<const u32x2*>(ps + (size_t)r0 * 768 + 256 + ch);
;   hxc = *reinterpret_cast<const u32x2*>(ps + (size_t)r0 * 768 + 512 + ch);
;   for (int tok = r0; tok < r1; ++tok) {
;     if (tok + 1 < TA) {
;       const bf16_t* np = ps + (size_t)(tok + 1) * 768 + ch;
;       gbn = *reinterpret_cast<const u32x2*>(np); gcn = *reinterpret_cast<const u32x2*>(np + 256); hxn = *reinterpret_cast<const u32x2*>(np + 512);
;     }
;     int ps_, sl;
;     if (tok < TL) { ps_ = tok & 63; sl = 64; } else { ps_ = (tok - TL) & 255; sl = 256; }
;     const float mp = (ps_ > 0) ? 1.f : 0.f, mn = (ps_ < sl - 1) ? 1.f : 0.f;
;     float v[4];
;     v[0] = lo2f(gbc.x) * (mp * w0[0] * lo2f(gcp.x) * lo2f(hxp.x) + w1[0] * lo2f(gcc.x) * lo2f(hxc.x) + mn * w2[0] * lo2f(gcn.x) * lo2f(hxn.x));
;     v[1] = hi2f(gbc.x) * (mp * w0[1] * hi2f(gcp.x) * hi2f(hxp.x) + w1[1] * hi2f(gcc.x) * hi2f(hxc.x) + mn * w2[1] * hi2f(gcn.x) * hi2f(hxn.x));
;     v[2] = lo2f(gbc.y) * (mp * w0[2] * lo2f(gcp.y) * lo2f(hxp.y) + w1[2] * lo2f(gcc.y) * lo2f(hxc.y) + mn * w2[2] * lo2f(gcn.y) * lo2f(hxn.y));
;     v[3] = hi2f(gbc.y) * (mp * w0[3] * hi2f(gcp.y) * hi2f(hxp.y) + w1[3] * hi2f(gcc.y) * hi2f(hxc.y) + mn * w2[3] * hi2f(gcn.y) * hi2f(hxn.y));
;     float ss = wave_sum(v[0] * v[0] + v[1] * v[1] + v[2] * v[2] + v[3] * v[3]);
;     const float rstd = rsqrtf(ss * (1.f / 256.f) + EPS);
;     *reinterpret_cast<u32x2*>(p.bufA + (size_t)tok * DM + 768 + ch) =
;         mk2(pk2(v[0] * rstd * gn[0], v[1] * rstd * gn[1]), pk2(v[2] * rstd * gn[2], v[3] * rstd * gn[3]));
;     gcp = gcc; hxp = hxc; gcc = gcn; hxc = hxn; gbc = gbn;
;   }
; }
.LBB0_553:
	s_or_b64 exec, exec, s[4:5]
	v_readlane_b32 s4, v248, 31
	v_readlane_b32 s5, v248, 32
	s_movk_i32 s6, 0x600
	v_lshlrev_b32_e32 v22, 1, v16
	v_mov_b64_e32 v[18:19], s[4:5]
	v_mad_i64_i32 v[18:19], s[0:1], v34, s6, v[18:19]
	v_mov_b32_e32 v23, v177
	v_lshl_add_u64 v[20:21], v[18:19], 0, v[22:23]
	global_load_dwordx2 v[16:17], v[20:21], off offset:1024
	global_load_dwordx2 v[18:19], v[20:21], off offset:512
	global_load_dwordx2 v[36:37], v[20:21], off
	v_ashrrev_i32_e32 v35, 31, v34
	v_lshlrev_b64 v[20:21], 11, v[34:35]
	v_readlane_b32 s0, v246, 56
	v_or_b32_e32 v20, v20, v22
	v_readlane_b32 s1, v246, 57
	v_add_u32_e32 v23, 1, v34
	v_mov_b64_e32 v[28:29], v[176:177]
	v_lshl_add_u64 v[20:21], s[0:1], 0, v[20:21]
	v_mad_i64_i32 v[24:25], s[0:1], v23, s6, 0
	v_or_b32_e32 v24, v24, v22
	v_lshl_add_u64 v[22:23], s[4:5], 0, v[24:25]
	s_mov_b64 s[4:5], 0
	v_mov_b64_e32 v[24:25], v[176:177]
	v_mov_b64_e32 v[26:27], v[176:177]
	v_mov_b64_e32 v[56:57], v[176:177]
	v_mov_b64_e32 v[58:59], v[176:177]
	v_mov_b64_e32 v[60:61], v[176:177]
	s_mov_b32 s0, 0x10fff
	v_cmp_gt_i32_e32 vcc, s0, v34
	s_and_saveexec_b64 s[6:7], vcc
	global_load_dwordx2 v[26:27], v[22:23], off
	global_load_dwordx2 v[24:25], v[22:23], off offset:512
	global_load_dwordx2 v[28:29], v[22:23], off offset:1024
	s_or_b64 exec, exec, s[6:7]
	s_mov_b64 s[0:1], 0x600
	v_lshl_add_u64 v[22:23], v[22:23], 0, s[0:1]
	s_waitcnt vmcnt(0)
	s_branch .LBB0_555
.LBB0_554:
	s_or_b64 exec, exec, s[6:7]
	s_mov_b32 s0, 0x10000
	v_cmp_gt_i32_e32 vcc, s0, v34
	v_add_u32_e32 v39, 1, v34
	s_nop 0
	v_lshlrev_b32_e32 v46, 16, v33
	v_cndmask_b32_e64 v35, v211, 63, vcc
	v_and_b32_e32 v40, v35, v34
	v_cmp_eq_u32_e32 vcc, 0, v40
	v_and_b32_e32 v47, 0xffff0000, v33
	s_nop 0
	v_lshlrev_b32_e32 v48, 16, v17
	v_cndmask_b32_e64 v34, 1.0, 0, vcc
	v_cmp_eq_u32_e32 vcc, v40, v35
	v_mbcnt_lo_u32_b32 v35, -1, 0
	v_mbcnt_hi_u32_b32 v35, -1, v35
	v_and_b32_e32 v49, 0xffff0000, v17
	v_lshlrev_b32_e32 v35, 2, v35
	v_pk_mul_f32 v[44:45], v[2:3], v[34:35] op_sel_hi:[1,0]
	v_cndmask_b32_e64 v40, 1.0, 0, vcc
	v_pk_mul_f32 v[44:45], v[44:45], v[46:47]
	v_lshlrev_b32_e32 v46, 16, v31
	v_and_b32_e32 v47, 0xffff0000, v31
	v_pk_mul_f32 v[44:45], v[44:45], v[46:47]
	s_nop 0
	v_lshlrev_b32_e32 v46, 16, v19
	v_and_b32_e32 v47, 0xffff0000, v19
	v_xor_b32_e32 v41, 0x80, v35
	v_pk_mul_f32 v[46:47], v[6:7], v[46:47]
	v_xor_b32_e32 v50, 64, v35
	v_pk_fma_f32 v[44:45], v[46:47], v[48:49], v[44:45]
	v_pk_mul_f32 v[46:47], v[10:11], v[40:41] op_sel_hi:[1,0]
	v_lshlrev_b32_e32 v48, 16, v25
	v_and_b32_e32 v49, 0xffff0000, v25
	v_pk_mul_f32 v[46:47], v[46:47], v[48:49]
	s_nop 0
	v_lshlrev_b32_e32 v48, 16, v29
	v_and_b32_e32 v49, 0xffff0000, v29
	v_xor_b32_e32 v51, 32, v35
	v_xor_b32_e32 v52, 16, v35
	v_xor_b32_e32 v53, 8, v35
	v_xor_b32_e32 v54, 4, v35
	v_lshlrev_b32_e32 v42, 16, v37
	v_and_b32_e32 v43, 0xffff0000, v37
	v_pk_fma_f32 v[44:45], v[46:47], v[48:49], v[44:45]
	v_lshlrev_b32_e32 v46, 16, v36
	v_and_b32_e32 v47, 0xffff0000, v36
	v_pk_mul_f32 v[34:35], v[0:1], v[34:35] op_sel_hi:[1,0]
	v_lshlrev_b32_e32 v36, 16, v32
	v_and_b32_e32 v37, 0xffff0000, v32
	v_pk_mul_f32 v[32:33], v[34:35], v[36:37]
	v_lshlrev_b32_e32 v34, 16, v30
	v_and_b32_e32 v35, 0xffff0000, v30
	v_pk_mul_f32 v[30:31], v[32:33], v[34:35]
	v_lshlrev_b32_e32 v32, 16, v18
	v_and_b32_e32 v33, 0xffff0000, v18
	v_pk_mul_f32 v[32:33], v[4:5], v[32:33]
	v_lshlrev_b32_e32 v34, 16, v16
	v_and_b32_e32 v35, 0xffff0000, v16
	v_pk_fma_f32 v[30:31], v[32:33], v[34:35], v[30:31]
	v_pk_mul_f32 v[32:33], v[8:9], v[40:41] op_sel_hi:[1,0]
	v_lshlrev_b32_e32 v34, 16, v24
	v_and_b32_e32 v35, 0xffff0000, v24
	v_pk_mul_f32 v[32:33], v[32:33], v[34:35]
	v_lshlrev_b32_e32 v34, 16, v28
	v_and_b32_e32 v35, 0xffff0000, v28
	v_pk_fma_f32 v[30:31], v[32:33], v[34:35], v[30:31]
	v_pk_mul_f32 v[42:43], v[44:45], v[42:43]
	v_pk_mul_f32 v[30:31], v[30:31], v[46:47]
	v_pk_mul_f32 v[44:45], v[42:43], v[42:43]
	v_pk_mul_f32 v[32:33], v[30:31], v[30:31]
	s_mov_b32 s0, 0x800000
	v_add_f32_e32 v32, v32, v33
	v_add_f32_e32 v32, v44, v32
	v_add_f32_e32 v32, v45, v32
	ds_bpermute_b32 v33, v41, v32
	v_mov_b64_e32 v[36:37], v[26:27]
	v_mov_b32_e32 v34, v39
	s_waitcnt lgkmcnt(0)
	v_add_f32_e32 v32, v32, v33
	ds_bpermute_b32 v33, v50, v32
	s_waitcnt lgkmcnt(0)
	v_add_f32_e32 v32, v32, v33
	ds_bpermute_b32 v33, v51, v32
	s_waitcnt lgkmcnt(0)
	v_add_f32_e32 v32, v32, v33
	ds_bpermute_b32 v33, v52, v32
	s_waitcnt lgkmcnt(0)
	v_add_f32_e32 v32, v32, v33
	ds_bpermute_b32 v33, v53, v32
	s_waitcnt lgkmcnt(0)
	v_add_f32_e32 v32, v32, v33
	ds_bpermute_b32 v33, v54, v32
	s_waitcnt lgkmcnt(0)
	v_add_f32_e32 v32, v32, v33
	v_fmamk_f32 v32, v32, 0x3b800000, v192
	v_cmp_gt_f32_e32 vcc, s0, v32
	v_mul_f32_e32 v33, 0x4b800000, v32
	s_mov_b64 s[0:1], 0x800
	v_cndmask_b32_e32 v32, v32, v33, vcc
	v_rsq_f32_e32 v32, v32
	s_nop 0
	v_mul_f32_e32 v33, 0x45800000, v32
	v_cndmask_b32_e32 v32, v32, v33, vcc
	v_pk_mul_f32 v[30:31], v[30:31], v[32:33] op_sel_hi:[1,0]
	v_pk_mul_f32 v[32:33], v[42:43], v[32:33] op_sel_hi:[1,0]
	v_pk_mul_f32 v[30:31], v[12:13], v[30:31]
	v_pk_mul_f32 v[32:33], v[14:15], v[32:33]
	v_cvt_pk_bf16_f32 v30, v30, v31
	v_cvt_pk_bf16_f32 v31, v32, v33
	global_store_dwordx2 v[20:21], v[30:31], off
	v_lshl_add_u64 v[20:21], v[20:21], 0, s[0:1]
	s_mov_b64 s[0:1], 0x600
	v_cmp_ge_i32_e32 vcc, v39, v38
	v_lshl_add_u64 v[22:23], v[22:23], 0, s[0:1]
	s_or_b64 s[4:5], vcc, s[4:5]
	s_waitcnt vmcnt(1)
	v_mov_b64_e32 v[32:33], v[18:19]
	v_mov_b64_e32 v[30:31], v[16:17]
	v_mov_b64_e32 v[18:19], v[24:25]
	v_mov_b64_e32 v[16:17], v[28:29]
	v_mov_b64_e32 v[26:27], v[56:57]
	v_mov_b64_e32 v[24:25], v[58:59]
	v_mov_b64_e32 v[28:29], v[60:61]
	s_andn2_b64 exec, exec, s[4:5]
	s_cbranch_execz .LBB0_557
.LBB0_555:
	s_mov_b32 s0, 0x10ffe
	v_cmp_gt_i32_e32 vcc, s0, v34
	s_and_saveexec_b64 s[6:7], vcc
	s_cbranch_execz .LBB0_554
	global_load_dwordx2 v[56:57], v[22:23], off
	global_load_dwordx2 v[58:59], v[22:23], off offset:512
	global_load_dwordx2 v[60:61], v[22:23], off offset:1024
	s_branch .LBB0_554

; __device__ __forceinline__ void prep_filter_item(const Params& p, int l, int it, char* smem, int wvi) {
;     ...
;   {
;     const float* W = p.fw1 + (size_t)l * 33 * 64; const float bb = p.fb1[l * 64 + u];
; #pragma unroll 1
;     for (int q = 0; q < 4; ++q) {
;       const int ps = pg * 4 + q; float a = bb;
;       for (int k = 0; k < 33; ++k) a += sF[ps * 33 + k] * W[k * 64 + u];
;       sH1[ps * 64 + u] = sinf(fr * a);
;     }
.LBB0_1088:
	v_lshl_add_u64 v[16:17], v[4:5], 0, s[2:3]
	global_load_dword v80, v[16:17], off
	global_load_dword v81, v[16:17], off offset:256
	global_load_dword v82, v[16:17], off offset:512
	global_load_dword v83, v[16:17], off offset:768
	global_load_dword v84, v[16:17], off offset:1024
	global_load_dword v85, v[16:17], off offset:1280
	global_load_dword v86, v[16:17], off offset:1536
	global_load_dword v87, v[16:17], off offset:1792
	global_load_dword v88, v[16:17], off offset:2048
	global_load_dword v89, v[16:17], off offset:2304
	global_load_dword v90, v[16:17], off offset:2560
	ds_read2_b32 v[14:15], v12 offset1:1
	s_add_u32 s2, s2, 0xb00
	s_addc_u32 s3, s3, 0
	s_cmpk_eq_i32 s2, 0x2100
	s_waitcnt vmcnt(10) lgkmcnt(0)
	v_fmac_f32_e32 v13, v14, v80
	s_waitcnt vmcnt(9)
	v_fmac_f32_e32 v13, v15, v81
	ds_read2_b32 v[14:15], v12 offset0:2 offset1:3
	s_waitcnt vmcnt(8) lgkmcnt(0)
	v_fmac_f32_e32 v13, v14, v82
	s_waitcnt vmcnt(7)
	v_fmac_f32_e32 v13, v15, v83
	ds_read2_b32 v[14:15], v12 offset0:4 offset1:5
	s_waitcnt vmcnt(6) lgkmcnt(0)
	v_fmac_f32_e32 v13, v14, v84
	s_waitcnt vmcnt(5)
	v_fmac_f32_e32 v13, v15, v85
	ds_read2_b32 v[14:15], v12 offset0:6 offset1:7
	s_waitcnt vmcnt(4) lgkmcnt(0)
	v_fmac_f32_e32 v13, v14, v86
	s_waitcnt vmcnt(3)
	v_fmac_f32_e32 v13, v15, v87
	ds_read2_b32 v[14:15], v12 offset0:8 offset1:9
	s_waitcnt vmcnt(2) lgkmcnt(0)
	v_fmac_f32_e32 v13, v14, v88
	s_waitcnt vmcnt(1)
	v_fmac_f32_e32 v13, v15, v89
	ds_read_b32 v14, v12 offset:40
	v_add_u32_e32 v12, 44, v12
	s_waitcnt vmcnt(0) lgkmcnt(0)
	v_fmac_f32_e32 v13, v14, v90
	s_cbranch_scc0 .LBB0_1088
	v_mul_f32_e32 v12, v7, v13
	v_and_b32_e32 v13, 0x7fffffff, v12
	v_cmp_nlt_f32_e64 s[2:3], |v12|, s23
	s_and_saveexec_b64 s[4:5], s[2:3]
	s_xor_b64 s[2:3], exec, s[4:5]
	s_cbranch_execz .LBB0_1091
	v_lshrrev_b32_e32 v14, 23, v13
	v_add_u32_e32 v14, 0xffffff88, v14
	v_cmp_lt_u32_e64 s[4:5], 63, v14
	s_nop 1
	v_cndmask_b32_e64 v15, 0, v203, s[4:5]
	v_add_u32_e32 v14, v15, v14
	v_cmp_lt_u32_e64 s[6:7], 31, v14
	s_nop 1
	v_cndmask_b32_e64 v15, 0, v204, s[6:7]
	v_add_u32_e32 v14, v15, v14
	v_cmp_lt_u32_e64 s[8:9], 31, v14
	s_nop 1
	v_cndmask_b32_e64 v15, 0, v204, s[8:9]
	v_add_u32_e32 v28, v15, v14
	v_and_b32_e32 v14, 0x7fffff, v13
	v_or_b32_e32 v26, 0x800000, v14
	v_mad_u64_u32 v[14:15], s[10:11], v26, s25, 0
	v_mov_b32_e32 v176, v15
	v_mad_u64_u32 v[16:17], s[10:11], v26, s26, v[176:177]
	v_mov_b32_e32 v176, v17
	v_mad_u64_u32 v[18:19], s[10:11], v26, s27, v[176:177]
	v_mov_b32_e32 v176, v19
	v_mad_u64_u32 v[20:21], s[10:11], v26, s30, v[176:177]
	v_mov_b32_e32 v176, v21
	v_mad_u64_u32 v[22:23], s[10:11], v26, s31, v[176:177]
	v_mov_b32_e32 v176, v23
	v_mad_u64_u32 v[24:25], s[10:11], v26, s34, v[176:177]
	v_mov_b32_e32 v176, v25
	v_mad_u64_u32 v[26:27], s[10:11], v26, s35, v[176:177]
	v_cndmask_b32_e64 v15, v24, v20, s[4:5]
	v_cndmask_b32_e64 v17, v26, v22, s[4:5]
	v_cndmask_b32_e64 v21, v27, v24, s[4:5]
	v_cndmask_b32_e64 v19, v17, v15, s[6:7]
	v_cndmask_b32_e64 v17, v21, v17, s[6:7]
	v_cndmask_b32_e64 v21, v22, v18, s[4:5]
	v_cndmask_b32_e64 v15, v15, v21, s[6:7]
	v_cndmask_b32_e64 v16, v20, v16, s[4:5]
	v_cndmask_b32_e64 v17, v17, v19, s[8:9]
	v_cndmask_b32_e64 v19, v19, v15, s[8:9]
	v_sub_u32_e32 v22, 32, v28
	v_cndmask_b32_e64 v20, v21, v16, s[6:7]
	v_alignbit_b32 v23, v17, v19, v22
	v_cmp_eq_u32_e64 s[10:11], 0, v28
	v_cndmask_b32_e64 v15, v15, v20, s[8:9]
	v_alignbit_b32 v21, v19, v15, v22
	v_cndmask_b32_e64 v17, v23, v17, s[10:11]
	v_cndmask_b32_e64 v14, v18, v14, s[4:5]
	v_cndmask_b32_e64 v19, v21, v19, s[10:11]
	v_bfe_u32 v24, v17, 29, 1
	v_cndmask_b32_e64 v14, v16, v14, s[6:7]
	v_alignbit_b32 v21, v17, v19, 30
	v_sub_u32_e32 v25, 0, v24
	v_cndmask_b32_e64 v14, v20, v14, s[8:9]
	v_xor_b32_e32 v21, v21, v25
	v_alignbit_b32 v16, v15, v14, v22
	v_cndmask_b32_e64 v15, v16, v15, s[10:11]
	v_ffbh_u32_e32 v18, v21
	v_alignbit_b32 v16, v19, v15, 30
	v_min_u32_e32 v18, 32, v18
	v_alignbit_b32 v14, v15, v14, 30
	v_xor_b32_e32 v16, v16, v25
	v_sub_u32_e32 v19, 31, v18
	v_xor_b32_e32 v14, v14, v25
	v_alignbit_b32 v20, v21, v16, v19
	v_alignbit_b32 v14, v16, v14, v19
	v_alignbit_b32 v15, v20, v14, 9
	v_ffbh_u32_e32 v16, v15
	v_min_u32_e32 v16, 32, v16
	v_lshrrev_b32_e32 v23, 29, v17
	v_not_b32_e32 v19, v16
	v_alignbit_b32 v14, v15, v14, v19
	v_lshlrev_b32_e32 v15, 31, v23
	v_or_b32_e32 v19, 0x33000000, v15
	v_add_lshl_u32 v16, v16, v18, 23
	v_lshrrev_b32_e32 v14, 9, v14
	v_sub_u32_e32 v16, v19, v16
	v_or_b32_e32 v15, 0.5, v15
	v_lshlrev_b32_e32 v18, 23, v18
	v_or_b32_e32 v14, v16, v14
	v_lshrrev_b32_e32 v16, 9, v20
	v_sub_u32_e32 v15, v15, v18
	v_or_b32_e32 v15, v16, v15
	v_mul_f32_e32 v16, 0x3fc90fda, v15
	v_fma_f32 v18, v15, s36, -v16
	v_fmac_f32_e32 v18, 0x33a22168, v15
	v_fmac_f32_e32 v18, 0x3fc90fda, v14
	v_lshrrev_b32_e32 v14, 30, v17
	v_add_f32_e32 v15, v16, v18
	v_add_u32_e32 v14, v24, v14

; __device__ __forceinline__ void prep_filter_item(const Params& p, int l, int it, char* smem, int wvi) {
;     ...
;   {
;     const float* W = p.fw2 + (size_t)l * 64 * 64; const float bb = p.fb2[l * 64 + u];
; #pragma unroll 1
;     for (int q = 0; q < 4; ++q) {
;       const int ps = pg * 4 + q; float a = bb;
;       for (int k = 0; k < 64; ++k) a += sH1[ps * 64 + k] * W[k * 64 + u];
;       sH2[ps * 64 + u] = sinf(fr * a);
;     }
;   }
.LBB0_1096:
	v_lshl_add_u64 v[14:15], v[2:3], 0, s[2:3]
	global_load_dword v80, v[14:15], off
	global_load_dword v81, v[14:15], off offset:256
	global_load_dword v82, v[14:15], off offset:512
	global_load_dword v83, v[14:15], off offset:768
	global_load_dword v84, v[14:15], off offset:1024
	global_load_dword v85, v[14:15], off offset:1280
	global_load_dword v86, v[14:15], off offset:1536
	global_load_dword v87, v[14:15], off offset:1792
	global_load_dword v88, v[14:15], off offset:2048
	global_load_dword v89, v[14:15], off offset:2304
	global_load_dword v90, v[14:15], off offset:2560
	global_load_dword v91, v[14:15], off offset:2816
	global_load_dword v92, v[14:15], off offset:3072
	global_load_dword v93, v[14:15], off offset:3328
	global_load_dword v94, v[14:15], off offset:3584
	global_load_dword v95, v[14:15], off offset:3840
	ds_read_b128 v[14:17], v13
	ds_read_b128 v[18:21], v13 offset:16
	ds_read_b128 v[22:25], v13 offset:32
	ds_read_b128 v[26:29], v13 offset:48
	s_add_u32 s2, s2, 0x1000
	s_addc_u32 s3, s3, 0
	v_add_u32_e32 v13, 64, v13
	s_cmpk_eq_i32 s2, 0x4000
	s_waitcnt vmcnt(15) lgkmcnt(3)
	v_fmac_f32_e32 v12, v14, v80
	s_waitcnt vmcnt(14)
	v_fmac_f32_e32 v12, v15, v81
	s_waitcnt vmcnt(13)
	v_fmac_f32_e32 v12, v16, v82
	s_waitcnt vmcnt(12)
	v_fmac_f32_e32 v12, v17, v83
	s_waitcnt vmcnt(11) lgkmcnt(2)
	v_fmac_f32_e32 v12, v18, v84
	s_waitcnt vmcnt(10)
	v_fmac_f32_e32 v12, v19, v85
	s_waitcnt vmcnt(9)
	v_fmac_f32_e32 v12, v20, v86
	s_waitcnt vmcnt(8)
	v_fmac_f32_e32 v12, v21, v87
	s_waitcnt vmcnt(7) lgkmcnt(1)
	v_fmac_f32_e32 v12, v22, v88
	s_waitcnt vmcnt(6)
	v_fmac_f32_e32 v12, v23, v89
	s_waitcnt vmcnt(5)
	v_fmac_f32_e32 v12, v24, v90
	s_waitcnt vmcnt(4)
	v_fmac_f32_e32 v12, v25, v91
	s_waitcnt vmcnt(3) lgkmcnt(0)
	v_fmac_f32_e32 v12, v26, v92
	s_waitcnt vmcnt(2)
	v_fmac_f32_e32 v12, v27, v93
	s_waitcnt vmcnt(1)
	v_fmac_f32_e32 v12, v28, v94
	s_waitcnt vmcnt(0)
	v_fmac_f32_e32 v12, v29, v95
	s_cbranch_scc0 .LBB0_1096
	v_mul_f32_e32 v12, v7, v12
	v_and_b32_e32 v13, 0x7fffffff, v12
	v_cmp_nlt_f32_e64 s[2:3], |v12|, s23
	s_and_saveexec_b64 s[4:5], s[2:3]
	s_xor_b64 s[2:3], exec, s[4:5]
	s_cbranch_execz .LBB0_1099
	v_lshrrev_b32_e32 v14, 23, v13
	v_add_u32_e32 v14, 0xffffff88, v14
	v_cmp_lt_u32_e64 s[4:5], 63, v14
	s_nop 1
	v_cndmask_b32_e64 v15, 0, v203, s[4:5]
	v_add_u32_e32 v14, v15, v14
	v_cmp_lt_u32_e64 s[6:7], 31, v14
	s_nop 1
	v_cndmask_b32_e64 v15, 0, v204, s[6:7]
	v_add_u32_e32 v14, v15, v14
	v_cmp_lt_u32_e64 s[8:9], 31, v14
	s_nop 1
	v_cndmask_b32_e64 v15, 0, v204, s[8:9]
	v_add_u32_e32 v28, v15, v14
	v_and_b32_e32 v14, 0x7fffff, v13
	v_or_b32_e32 v26, 0x800000, v14
	v_mad_u64_u32 v[14:15], s[10:11], v26, s25, 0
	v_mov_b32_e32 v176, v15
	v_mad_u64_u32 v[16:17], s[10:11], v26, s26, v[176:177]
	v_mov_b32_e32 v176, v17
	v_mad_u64_u32 v[18:19], s[10:11], v26, s27, v[176:177]
	v_mov_b32_e32 v176, v19
	v_mad_u64_u32 v[20:21], s[10:11], v26, s30, v[176:177]
	v_mov_b32_e32 v176, v21
	v_mad_u64_u32 v[22:23], s[10:11], v26, s31, v[176:177]
	v_mov_b32_e32 v176, v23
	v_mad_u64_u32 v[24:25], s[10:11], v26, s34, v[176:177]
	v_mov_b32_e32 v176, v25
	v_mad_u64_u32 v[26:27], s[10:11], v26, s35, v[176:177]
	v_cndmask_b32_e64 v15, v24, v20, s[4:5]
	v_cndmask_b32_e64 v17, v26, v22, s[4:5]
	v_cndmask_b32_e64 v21, v27, v24, s[4:5]
	v_cndmask_b32_e64 v19, v17, v15, s[6:7]
	v_cndmask_b32_e64 v17, v21, v17, s[6:7]
	v_cndmask_b32_e64 v21, v22, v18, s[4:5]
	v_cndmask_b32_e64 v15, v15, v21, s[6:7]
	v_cndmask_b32_e64 v16, v20, v16, s[4:5]
	v_cndmask_b32_e64 v17, v17, v19, s[8:9]
	v_cndmask_b32_e64 v19, v19, v15, s[8:9]
	v_sub_u32_e32 v22, 32, v28
	v_cndmask_b32_e64 v20, v21, v16, s[6:7]
	v_alignbit_b32 v23, v17, v19, v22
	v_cmp_eq_u32_e64 s[10:11], 0, v28
	v_cndmask_b32_e64 v15, v15, v20, s[8:9]
	v_alignbit_b32 v21, v19, v15, v22
	v_cndmask_b32_e64 v17, v23, v17, s[10:11]
	v_cndmask_b32_e64 v14, v18, v14, s[4:5]
	v_cndmask_b32_e64 v19, v21, v19, s[10:11]
	v_bfe_u32 v24, v17, 29, 1
	v_cndmask_b32_e64 v14, v16, v14, s[6:7]
	v_alignbit_b32 v21, v17, v19, 30
	v_sub_u32_e32 v25, 0, v24
	v_cndmask_b32_e64 v14, v20, v14, s[8:9]
	v_xor_b32_e32 v21, v21, v25
	v_alignbit_b32 v16, v15, v14, v22
	v_cndmask_b32_e64 v15, v16, v15, s[10:11]
	v_ffbh_u32_e32 v18, v21
	v_alignbit_b32 v16, v19, v15, 30
	v_min_u32_e32 v18, 32, v18
	v_alignbit_b32 v14, v15, v14, 30
	v_xor_b32_e32 v16, v16, v25
	v_sub_u32_e32 v19, 31, v18
	v_xor_b32_e32 v14, v14, v25
	v_alignbit_b32 v20, v21, v16, v19
	v_alignbit_b32 v14, v16, v14, v19
	v_alignbit_b32 v15, v20, v14, 9
	v_ffbh_u32_e32 v16, v15
	v_min_u32_e32 v16, 32, v16
	v_lshrrev_b32_e32 v23, 29, v17
	v_not_b32_e32 v19, v16
	v_alignbit_b32 v14, v15, v14, v19
	v_lshlrev_b32_e32 v15, 31, v23
	v_or_b32_e32 v19, 0x33000000, v15
	v_add_lshl_u32 v16, v16, v18, 23
	v_lshrrev_b32_e32 v14, 9, v14
	v_sub_u32_e32 v16, v19, v16
	v_or_b32_e32 v15, 0.5, v15
	v_lshlrev_b32_e32 v18, 23, v18
	v_or_b32_e32 v14, v16, v14
	v_lshrrev_b32_e32 v16, 9, v20
	v_sub_u32_e32 v15, v15, v18
	v_or_b32_e32 v15, v16, v15
	v_mul_f32_e32 v16, 0x3fc90fda, v15
	v_fma_f32 v18, v15, s36, -v16
	v_fmac_f32_e32 v18, 0x33a22168, v15
	v_fmac_f32_e32 v18, 0x3fc90fda, v14
	v_lshrrev_b32_e32 v14, 30, v17
	v_add_f32_e32 v15, v16, v18
	v_add_u32_e32 v14, v24, v14

; __device__ __forceinline__ void prep_filter_item(const Params& p, int l, int it, char* smem, int wvi) {
;     ...
;   {
;     const float* W = p.fw3 + (size_t)l * 64 * 64; const float bb = p.fb3[l * 64 + u];
; #pragma unroll 1
;     for (int q = 0; q < 4; ++q) {
;       const int ps = pg * 4 + q; float a = bb;
;       for (int k = 0; k < 64; ++k) a += sH2[ps * 64 + k] * W[k * 64 + u];
;       sH3[ps * 64 + u] = sinf(fr * a);
;     }
;   }
.LBB0_1104:
	v_lshl_add_u64 v[10:11], v[0:1], 0, s[2:3]
	global_load_dword v80, v[10:11], off
	global_load_dword v81, v[10:11], off offset:256
	global_load_dword v82, v[10:11], off offset:512
	global_load_dword v83, v[10:11], off offset:768
	global_load_dword v84, v[10:11], off offset:1024
	global_load_dword v85, v[10:11], off offset:1280
	global_load_dword v86, v[10:11], off offset:1536
	global_load_dword v87, v[10:11], off offset:1792
	global_load_dword v88, v[10:11], off offset:2048
	global_load_dword v89, v[10:11], off offset:2304
	global_load_dword v90, v[10:11], off offset:2560
	global_load_dword v91, v[10:11], off offset:2816
	global_load_dword v92, v[10:11], off offset:3072
	global_load_dword v93, v[10:11], off offset:3328
	global_load_dword v94, v[10:11], off offset:3584
	global_load_dword v95, v[10:11], off offset:3840
	ds_read_b128 v[10:13], v5
	ds_read_b128 v[14:17], v5 offset:16
	ds_read_b128 v[18:21], v5 offset:32
	ds_read_b128 v[22:25], v5 offset:48
	s_add_u32 s2, s2, 0x1000
	s_addc_u32 s3, s3, 0
	v_add_u32_e32 v5, 64, v5
	s_cmpk_eq_i32 s2, 0x4000
	s_waitcnt vmcnt(15) lgkmcnt(3)
	v_fmac_f32_e32 v4, v10, v80
	s_waitcnt vmcnt(14)
	v_fmac_f32_e32 v4, v11, v81
	s_waitcnt vmcnt(13)
	v_fmac_f32_e32 v4, v12, v82
	s_waitcnt vmcnt(12)
	v_fmac_f32_e32 v4, v13, v83
	s_waitcnt vmcnt(11) lgkmcnt(2)
	v_fmac_f32_e32 v4, v14, v84
	s_waitcnt vmcnt(10)
	v_fmac_f32_e32 v4, v15, v85
	s_waitcnt vmcnt(9)
	v_fmac_f32_e32 v4, v16, v86
	s_waitcnt vmcnt(8)
	v_fmac_f32_e32 v4, v17, v87
	s_waitcnt vmcnt(7) lgkmcnt(1)
	v_fmac_f32_e32 v4, v18, v88
	s_waitcnt vmcnt(6)
	v_fmac_f32_e32 v4, v19, v89
	s_waitcnt vmcnt(5)
	v_fmac_f32_e32 v4, v20, v90
	s_waitcnt vmcnt(4)
	v_fmac_f32_e32 v4, v21, v91
	s_waitcnt vmcnt(3) lgkmcnt(0)
	v_fmac_f32_e32 v4, v22, v92
	s_waitcnt vmcnt(2)
	v_fmac_f32_e32 v4, v23, v93
	s_waitcnt vmcnt(1)
	v_fmac_f32_e32 v4, v24, v94
	s_waitcnt vmcnt(0)
	v_fmac_f32_e32 v4, v25, v95
	s_cbranch_scc0 .LBB0_1104
	v_mul_f32_e32 v4, v7, v4
	v_and_b32_e32 v5, 0x7fffffff, v4
	v_cmp_nlt_f32_e64 s[2:3], |v4|, s23
	s_and_saveexec_b64 s[4:5], s[2:3]
	s_xor_b64 s[2:3], exec, s[4:5]
	s_cbranch_execz .LBB0_1107
	v_lshrrev_b32_e32 v10, 23, v5
	v_add_u32_e32 v10, 0xffffff88, v10
	v_cmp_lt_u32_e64 s[4:5], 63, v10
	s_nop 1
	v_cndmask_b32_e64 v11, 0, v203, s[4:5]
	v_add_u32_e32 v10, v11, v10
	v_cmp_lt_u32_e64 s[6:7], 31, v10
	s_nop 1
	v_cndmask_b32_e64 v11, 0, v204, s[6:7]
	v_add_u32_e32 v10, v11, v10
	v_cmp_lt_u32_e64 s[8:9], 31, v10
	s_nop 1
	v_cndmask_b32_e64 v11, 0, v204, s[8:9]
	v_add_u32_e32 v24, v11, v10
	v_and_b32_e32 v10, 0x7fffff, v5
	v_or_b32_e32 v22, 0x800000, v10
	v_mad_u64_u32 v[10:11], s[10:11], v22, s25, 0
	v_mov_b32_e32 v176, v11
	v_mad_u64_u32 v[12:13], s[10:11], v22, s26, v[176:177]
	v_mov_b32_e32 v176, v13
	v_mad_u64_u32 v[14:15], s[10:11], v22, s27, v[176:177]
	v_mov_b32_e32 v176, v15
	v_mad_u64_u32 v[16:17], s[10:11], v22, s30, v[176:177]
	v_mov_b32_e32 v176, v17
	v_mad_u64_u32 v[18:19], s[10:11], v22, s31, v[176:177]
	v_mov_b32_e32 v176, v19
	v_mad_u64_u32 v[20:21], s[10:11], v22, s34, v[176:177]
	v_mov_b32_e32 v176, v21
	v_mad_u64_u32 v[22:23], s[10:11], v22, s35, v[176:177]
	v_cndmask_b32_e64 v11, v20, v16, s[4:5]
	v_cndmask_b32_e64 v13, v22, v18, s[4:5]
	v_cndmask_b32_e64 v17, v23, v20, s[4:5]
	v_cndmask_b32_e64 v15, v13, v11, s[6:7]
	v_cndmask_b32_e64 v13, v17, v13, s[6:7]
	v_cndmask_b32_e64 v17, v18, v14, s[4:5]
	v_cndmask_b32_e64 v11, v11, v17, s[6:7]
	v_cndmask_b32_e64 v12, v16, v12, s[4:5]
	v_cndmask_b32_e64 v13, v13, v15, s[8:9]
	v_cndmask_b32_e64 v15, v15, v11, s[8:9]
	v_sub_u32_e32 v18, 32, v24
	v_cndmask_b32_e64 v16, v17, v12, s[6:7]
	v_alignbit_b32 v19, v13, v15, v18
	v_cmp_eq_u32_e64 s[10:11], 0, v24
	v_cndmask_b32_e64 v11, v11, v16, s[8:9]
	v_alignbit_b32 v17, v15, v11, v18
	v_cndmask_b32_e64 v13, v19, v13, s[10:11]
	v_cndmask_b32_e64 v10, v14, v10, s[4:5]
	v_cndmask_b32_e64 v15, v17, v15, s[10:11]
	v_bfe_u32 v20, v13, 29, 1
	v_cndmask_b32_e64 v10, v12, v10, s[6:7]
	v_alignbit_b32 v17, v13, v15, 30
	v_sub_u32_e32 v21, 0, v20
	v_cndmask_b32_e64 v10, v16, v10, s[8:9]
	v_xor_b32_e32 v17, v17, v21
	v_alignbit_b32 v12, v11, v10, v18
	v_cndmask_b32_e64 v11, v12, v11, s[10:11]
	v_ffbh_u32_e32 v14, v17
	v_alignbit_b32 v12, v15, v11, 30
	v_min_u32_e32 v14, 32, v14
	v_alignbit_b32 v10, v11, v10, 30
	v_xor_b32_e32 v12, v12, v21
	v_sub_u32_e32 v15, 31, v14
	v_xor_b32_e32 v10, v10, v21
	v_alignbit_b32 v16, v17, v12, v15
	v_alignbit_b32 v10, v12, v10, v15
	v_alignbit_b32 v11, v16, v10, 9
	v_ffbh_u32_e32 v12, v11
	v_min_u32_e32 v12, 32, v12
	v_lshrrev_b32_e32 v19, 29, v13
	v_not_b32_e32 v15, v12
	v_alignbit_b32 v10, v11, v10, v15
	v_lshlrev_b32_e32 v11, 31, v19
	v_or_b32_e32 v15, 0x33000000, v11
	v_add_lshl_u32 v12, v12, v14, 23
	v_lshrrev_b32_e32 v10, 9, v10
	v_sub_u32_e32 v12, v15, v12
	v_or_b32_e32 v11, 0.5, v11
	v_lshlrev_b32_e32 v14, 23, v14
	v_or_b32_e32 v10, v12, v10
	v_lshrrev_b32_e32 v12, 9, v16
	v_sub_u32_e32 v11, v11, v14
	v_or_b32_e32 v11, v12, v11
	v_mul_f32_e32 v12, 0x3fc90fda, v11
	v_fma_f32 v14, v11, s36, -v12
	v_fmac_f32_e32 v14, 0x33a22168, v11
	v_fmac_f32_e32 v14, 0x3fc90fda, v10
	v_lshrrev_b32_e32 v10, 30, v13
	v_add_f32_e32 v11, v12, v14
	v_add_u32_e32 v10, v20, v10

; __device__ __forceinline__ void prep_filter_item(const Params& p, int l, int it, char* smem, int wvi) {
;     ...
;   for (int cc = 0; cc < 4; ++cc) {
;     const int col = tid + 256 * cc;
;     const int o = col >> 9, dr = (col >> 8) & 1, ch = col & 255;
;     const float dl = fabsf(a0 + (float)ch * ((a1 - a0) / 255.f));
;     for (int half = 0; half < 2; ++half) {
;       float acc[8];
; #pragma unroll
;       for (int q = 0; q < 8; ++q) acc[q] = 0.f;
;       for (int k = 0; k < 64; ++k) {
;         const float wv = W4[k * 1024 + col];
; #pragma unroll
;         for (int q = 0; q < 8; ++q) acc[q] += sH3[(half * 8 + q) * 64 + k] * wv;
;       }
; #pragma unroll
;       for (int q = 0; q < 8; ++q) {
;         const int i = pos0 + half * 8 + q;
;         const float t = (float)i * inv_lm1;
;         const float v = acc[q] * expf(-t * dl);
;         float* kb = (L == SEQ) ? p.kfl + (size_t)(o * 256 + ch) * 8192 : p.kfc + (size_t)(o * 256 + ch) * 512;
;         const int mid = (L == SEQ) ? 4096 : 256;
;         const int idx = (dr == 0) ? mid + i : ((i >= 1) ? mid - i : 0);
;         kb[idx] = v;
;       }
.LBB0_1111:
	global_load_dword v40, v[36:37], off
	v_add_u32_e32 v84, s4, v33
	v_add_u32_e32 v86, 0x400, v84
	v_ashrrev_i32_e32 v87, 31, v86
	v_lshl_add_u64 v[86:87], v[86:87], 2, s[74:75]
	global_load_dword v90, v[86:87], off
	v_add_u32_e32 v88, 0x800, v84
	v_ashrrev_i32_e32 v89, 31, v88
	v_lshl_add_u64 v[88:89], v[88:89], 2, s[74:75]
	global_load_dword v92, v[88:89], off
	v_add_u32_e32 v96, 0xc00, v84
	v_ashrrev_i32_e32 v97, 31, v96
	v_lshl_add_u64 v[96:97], v[96:97], 2, s[74:75]
	global_load_dword v94, v[96:97], off
	v_mov_b32_e32 v28, s5
	ds_read_b128 v[0:3], v28
	ds_read_b128 v[4:7], v28 offset:256
	s_add_i32 s5, s5, 16
	v_lshl_add_u64 v[36:37], v[36:37], 0, s[84:85]
	s_waitcnt lgkmcnt(1)
	v_mov_b32_e32 v10, v0
	s_waitcnt lgkmcnt(0)
	v_mov_b32_e32 v11, v4
	v_mov_b32_e32 v4, v1
	s_waitcnt vmcnt(3)
	v_pk_fma_f32 v[60:61], v[40:41], v[10:11], v[8:9] op_sel_hi:[0,1,1]
	ds_read_b128 v[8:11], v28 offset:512
	ds_read_b128 v[12:15], v28 offset:768
	s_waitcnt lgkmcnt(1)
	v_mov_b32_e32 v18, v8
	s_waitcnt lgkmcnt(0)
	v_mov_b32_e32 v19, v12
	v_pk_fma_f32 v[62:63], v[40:41], v[18:19], v[16:17] op_sel_hi:[0,1,1]
	ds_read_b128 v[16:19], v28 offset:1024
	ds_read_b128 v[20:23], v28 offset:1280
	v_mov_b32_e32 v12, v9
	s_waitcnt lgkmcnt(1)
	v_mov_b32_e32 v26, v16
	s_waitcnt lgkmcnt(0)
	v_mov_b32_e32 v27, v20
	v_pk_fma_f32 v[64:65], v[40:41], v[26:27], v[24:25] op_sel_hi:[0,1,1]
	ds_read_b128 v[24:27], v28 offset:1536
	ds_read_b128 v[28:31], v28 offset:1792
	v_mov_b32_e32 v20, v17
	s_waitcnt lgkmcnt(1)
	v_mov_b32_e32 v66, v24
	s_waitcnt lgkmcnt(0)
	v_mov_b32_e32 v67, v28
	v_pk_fma_f32 v[38:39], v[40:41], v[66:67], v[38:39] op_sel_hi:[0,1,1]
	v_mov_b32_e32 v28, v25
	s_addk_i32 s4, 0x1000
	s_cmp_eq_u32 s4, 0x10000
	s_waitcnt vmcnt(2)
	v_pk_fma_f32 v[4:5], v[90:91], v[4:5], v[60:61] op_sel_hi:[0,1,1]
	v_pk_fma_f32 v[8:9], v[90:91], v[12:13], v[62:63] op_sel_hi:[0,1,1]
	v_pk_fma_f32 v[12:13], v[90:91], v[20:21], v[64:65] op_sel_hi:[0,1,1]
	v_mov_b32_e32 v20, v2
	v_mov_b32_e32 v21, v6
	s_waitcnt vmcnt(1)
	v_pk_fma_f32 v[4:5], v[92:93], v[20:21], v[4:5] op_sel_hi:[0,1,1]
	v_mov_b32_e32 v20, v10
	v_mov_b32_e32 v21, v14
	v_pk_fma_f32 v[20:21], v[92:93], v[20:21], v[8:9] op_sel_hi:[0,1,1]
	v_mov_b32_e32 v8, v18
	v_mov_b32_e32 v9, v22
	v_pk_fma_f32 v[0:1], v[90:91], v[28:29], v[38:39] op_sel_hi:[0,1,1]
	v_pk_fma_f32 v[12:13], v[92:93], v[8:9], v[12:13] op_sel_hi:[0,1,1]
	v_mov_b32_e32 v8, v26
	v_mov_b32_e32 v9, v30
	v_pk_fma_f32 v[0:1], v[92:93], v[8:9], v[0:1] op_sel_hi:[0,1,1]
	v_mov_b32_e32 v6, v3
	v_mov_b32_e32 v14, v11
	v_mov_b32_e32 v22, v19
	v_mov_b32_e32 v30, v27
	s_waitcnt vmcnt(0)
	v_pk_fma_f32 v[8:9], v[94:95], v[6:7], v[4:5] op_sel_hi:[0,1,1]
	v_pk_fma_f32 v[16:17], v[94:95], v[14:15], v[20:21] op_sel_hi:[0,1,1]
	v_pk_fma_f32 v[24:25], v[94:95], v[22:23], v[12:13] op_sel_hi:[0,1,1]
	v_pk_fma_f32 v[38:39], v[94:95], v[30:31], v[0:1] op_sel_hi:[0,1,1]
	s_cbranch_scc0 .LBB0_1111
	v_lshl_add_u32 v2, s6, 8, v32
	v_ashrrev_i32_e32 v0, 1, v2
	s_movk_i32 s4, 0xff00
	v_and_or_b32 v0, v0, s4, v42
	v_ashrrev_i32_e32 v1, 31, v0
	v_readlane_b32 s36, v245, 51
	v_and_b32_e32 v4, 0x100, v2
	v_lshlrev_b64 v[2:3], 11, v[0:1]
	v_lshlrev_b64 v[0:1], 15, v[0:1]
	v_readlane_b32 s38, v245, 53
	v_readlane_b32 s39, v245, 54
	v_readlane_b32 s40, v245, 55
	v_readlane_b32 s41, v245, 56
	v_lshl_add_u64 v[0:1], s[38:39], 0, v[0:1]
	v_cmp_eq_u32_e64 s[4:5], 0, v4
	v_lshl_add_u64 v[2:3], s[40:41], 0, v[2:3]
	v_cndmask_b32_e32 v37, v3, v1, vcc
	v_cndmask_b32_e32 v36, v2, v0, vcc
	v_mov_b32_e32 v0, s3
	v_mov_b32_e32 v1, s2
	v_cndmask_b32_e64 v0, v0, v1, s[4:5]
	v_ashrrev_i32_e32 v1, 31, v0
	v_mul_f32_e32 v4, v43, v8
	v_lshl_add_u64 v[0:1], v[0:1], 2, v[36:37]
	global_store_dword v[0:1], v4, off
	v_mov_b32_e32 v0, s24
	v_mov_b32_e32 v1, s7
	v_cndmask_b32_e64 v0, v0, v1, s[4:5]
	v_ashrrev_i32_e32 v1, 31, v0
	v_mul_f32_e32 v2, v44, v9
	v_lshl_add_u64 v[0:1], v[0:1], 2, v[36:37]
	global_store_dword v[0:1], v2, off
	v_mov_b32_e32 v0, s25
	v_mov_b32_e32 v1, s8
	v_cndmask_b32_e64 v0, v0, v1, s[4:5]
	v_ashrrev_i32_e32 v1, 31, v0
	v_mul_f32_e32 v2, v45, v16
	v_lshl_add_u64 v[0:1], v[0:1], 2, v[36:37]
	global_store_dword v[0:1], v2, off
	v_mov_b32_e32 v0, s26
	v_mov_b32_e32 v1, s9
	v_cndmask_b32_e64 v0, v0, v1, s[4:5]
	v_ashrrev_i32_e32 v1, 31, v0
	v_mul_f32_e32 v2, v46, v17
	v_lshl_add_u64 v[0:1], v[0:1], 2, v[36:37]
	global_store_dword v[0:1], v2, off
	v_mov_b32_e32 v0, s27
	v_mov_b32_e32 v1, s10
	v_cndmask_b32_e64 v0, v0, v1, s[4:5]
	v_ashrrev_i32_e32 v1, 31, v0
	v_mul_f32_e32 v2, v47, v24
	v_lshl_add_u64 v[0:1], v[0:1], 2, v[36:37]
	global_store_dword v[0:1], v2, off
	v_mov_b32_e32 v0, s28
	v_mov_b32_e32 v1, s11
	v_cndmask_b32_e64 v0, v0, v1, s[4:5]
	v_ashrrev_i32_e32 v1, 31, v0
	v_mul_f32_e32 v2, v48, v25
	v_lshl_add_u64 v[0:1], v[0:1], 2, v[36:37]
	global_store_dword v[0:1], v2, off
	v_mov_b32_e32 v0, s29
	v_mov_b32_e32 v1, s31
	v_cndmask_b32_e64 v0, v0, v1, s[4:5]
	v_ashrrev_i32_e32 v1, 31, v0
	v_mul_f32_e32 v2, v49, v38
	v_lshl_add_u64 v[0:1], v[0:1], 2, v[36:37]
	global_store_dword v[0:1], v2, off
	v_mov_b32_e32 v0, s55
	v_mov_b32_e32 v1, s34
	v_cndmask_b32_e64 v0, v0, v1, s[4:5]
	v_ashrrev_i32_e32 v1, 31, v0
	v_mov_b32_e32 v40, 0
	s_mov_b32 s67, 0
	v_mul_f32_e32 v2, v50, v39
	v_lshl_add_u64 v[0:1], v[0:1], 2, v[36:37]
	v_mov_b64_e32 v[38:39], v[34:35]
	v_readlane_b32 s96, v246, 37
	v_mov_b32_e32 v41, v40
	v_mov_b32_e32 v8, v40
	v_mov_b32_e32 v9, v40
	v_mov_b32_e32 v16, v40
	v_mov_b32_e32 v17, v40
	v_mov_b32_e32 v24, v40
	v_mov_b32_e32 v25, v40
	v_readlane_b32 s37, v245, 52
	v_readlane_b32 s42, v245, 57
	v_readlane_b32 s43, v245, 58
	global_store_dword v[0:1], v2, off
; __device__ __forceinline__ void prep_filter_item(const Params& p, int l, int it, char* smem, int wvi) {
;     ...
;   for (int cc = 0; cc < 4; ++cc) {
;     const int col = tid + 256 * cc;
;     const int o = col >> 9, dr = (col >> 8) & 1, ch = col & 255;
;     const float dl = fabsf(a0 + (float)ch * ((a1 - a0) / 255.f));
;     for (int half = 0; half < 2; ++half) {
;       float acc[8];
; #pragma unroll
;       for (int q = 0; q < 8; ++q) acc[q] = 0.f;
;       for (int k = 0; k < 64; ++k) {
;         const float wv = W4[k * 1024 + col];
; #pragma unroll
;         for (int q = 0; q < 8; ++q) acc[q] += sH3[(half * 8 + q) * 64 + k] * wv;
;       }
; #pragma unroll
;       for (int q = 0; q < 8; ++q) {
;         const int i = pos0 + half * 8 + q;
;         const float t = (float)i * inv_lm1;
;         const float v = acc[q] * expf(-t * dl);
;         float* kb = (L == SEQ) ? p.kfl + (size_t)(o * 256 + ch) * 8192 : p.kfc + (size_t)(o * 256 + ch) * 512;
;         const int mid = (L == SEQ) ? 4096 : 256;
;         const int idx = (dr == 0) ? mid + i : ((i >= 1) ? mid - i : 0);
;         kb[idx] = v;
;       }
.LBB0_1113:
	global_load_dword v60, v[38:39], off
	v_add_u32_e32 v84, s67, v33
	v_add_u32_e32 v86, 0x400, v84
	v_ashrrev_i32_e32 v87, 31, v86
	v_lshl_add_u64 v[86:87], v[86:87], 2, s[74:75]
	global_load_dword v90, v[86:87], off
	v_add_u32_e32 v88, 0x800, v84
	v_ashrrev_i32_e32 v89, 31, v88
	v_lshl_add_u64 v[88:89], v[88:89], 2, s[74:75]
	global_load_dword v92, v[88:89], off
	v_add_u32_e32 v96, 0xc00, v84
	v_ashrrev_i32_e32 v97, 31, v96
	v_lshl_add_u64 v[96:97], v[96:97], 2, s[74:75]
	global_load_dword v94, v[96:97], off
	v_mov_b32_e32 v28, s96
	ds_read_b128 v[0:3], v28
	ds_read_b128 v[4:7], v28 offset:256
	s_add_i32 s96, s96, 16
	v_lshl_add_u64 v[38:39], v[38:39], 0, s[84:85]
	s_waitcnt lgkmcnt(1)
	v_mov_b32_e32 v10, v0
	s_waitcnt lgkmcnt(0)
	v_mov_b32_e32 v11, v4
	v_mov_b32_e32 v4, v1
	s_waitcnt vmcnt(3)
	v_pk_fma_f32 v[62:63], v[60:61], v[10:11], v[8:9] op_sel_hi:[0,1,1]
	ds_read_b128 v[8:11], v28 offset:512
	ds_read_b128 v[12:15], v28 offset:768
	s_waitcnt lgkmcnt(1)
	v_mov_b32_e32 v18, v8
	s_waitcnt lgkmcnt(0)
	v_mov_b32_e32 v19, v12
	v_pk_fma_f32 v[64:65], v[60:61], v[18:19], v[16:17] op_sel_hi:[0,1,1]
	ds_read_b128 v[16:19], v28 offset:1024
	ds_read_b128 v[20:23], v28 offset:1280
	v_mov_b32_e32 v12, v9
	s_waitcnt lgkmcnt(1)
	v_mov_b32_e32 v26, v16
	s_waitcnt lgkmcnt(0)
	v_mov_b32_e32 v27, v20
	v_pk_fma_f32 v[66:67], v[60:61], v[26:27], v[24:25] op_sel_hi:[0,1,1]
	ds_read_b128 v[24:27], v28 offset:1536
	ds_read_b128 v[28:31], v28 offset:1792
	v_mov_b32_e32 v20, v17
	s_waitcnt lgkmcnt(1)
	v_mov_b32_e32 v68, v24
	s_waitcnt lgkmcnt(0)
	v_mov_b32_e32 v69, v28
	v_pk_fma_f32 v[40:41], v[60:61], v[68:69], v[40:41] op_sel_hi:[0,1,1]
	v_mov_b32_e32 v28, v25
	s_addk_i32 s67, 0x1000
	s_cmp_lg_u32 s67, 0x10000
	s_waitcnt vmcnt(2)
	v_pk_fma_f32 v[4:5], v[90:91], v[4:5], v[62:63] op_sel_hi:[0,1,1]
	v_pk_fma_f32 v[8:9], v[90:91], v[12:13], v[64:65] op_sel_hi:[0,1,1]
	v_pk_fma_f32 v[12:13], v[90:91], v[20:21], v[66:67] op_sel_hi:[0,1,1]
	v_mov_b32_e32 v20, v2
	v_mov_b32_e32 v21, v6
	s_waitcnt vmcnt(1)
	v_pk_fma_f32 v[4:5], v[92:93], v[20:21], v[4:5] op_sel_hi:[0,1,1]
	v_mov_b32_e32 v20, v10
	v_mov_b32_e32 v21, v14
	v_pk_fma_f32 v[20:21], v[92:93], v[20:21], v[8:9] op_sel_hi:[0,1,1]
	v_mov_b32_e32 v8, v18
	v_mov_b32_e32 v9, v22
	v_pk_fma_f32 v[0:1], v[90:91], v[28:29], v[40:41] op_sel_hi:[0,1,1]
	v_pk_fma_f32 v[12:13], v[92:93], v[8:9], v[12:13] op_sel_hi:[0,1,1]
	v_mov_b32_e32 v8, v26
	v_mov_b32_e32 v9, v30
	v_pk_fma_f32 v[0:1], v[92:93], v[8:9], v[0:1] op_sel_hi:[0,1,1]
	v_mov_b32_e32 v6, v3
	v_mov_b32_e32 v14, v11
	v_mov_b32_e32 v22, v19
	v_mov_b32_e32 v30, v27
	s_waitcnt vmcnt(0)
	v_pk_fma_f32 v[8:9], v[94:95], v[6:7], v[4:5] op_sel_hi:[0,1,1]
	v_pk_fma_f32 v[16:17], v[94:95], v[14:15], v[20:21] op_sel_hi:[0,1,1]
	v_pk_fma_f32 v[24:25], v[94:95], v[22:23], v[12:13] op_sel_hi:[0,1,1]
	v_pk_fma_f32 v[40:41], v[94:95], v[30:31], v[0:1] op_sel_hi:[0,1,1]
	s_cbranch_scc1 .LBB0_1113
	v_mov_b32_e32 v0, s88
	v_mov_b32_e32 v1, s14
	v_cndmask_b32_e64 v0, v0, v1, s[4:5]
	v_ashrrev_i32_e32 v1, 31, v0
	v_mul_f32_e32 v2, v51, v8
	v_lshl_add_u64 v[0:1], v[0:1], 2, v[36:37]
	global_store_dword v[0:1], v2, off
	v_mov_b32_e32 v0, s89
	v_mov_b32_e32 v1, s52
	v_cndmask_b32_e64 v0, v0, v1, s[4:5]
	v_ashrrev_i32_e32 v1, 31, v0
	v_mul_f32_e32 v2, v52, v9
	v_lshl_add_u64 v[0:1], v[0:1], 2, v[36:37]
	global_store_dword v[0:1], v2, off
	v_mov_b32_e32 v0, s92
	v_mov_b32_e32 v1, s16
	v_cndmask_b32_e64 v0, v0, v1, s[4:5]
	v_ashrrev_i32_e32 v1, 31, v0
	v_mul_f32_e32 v2, v53, v16
	v_lshl_add_u64 v[0:1], v[0:1], 2, v[36:37]
	global_store_dword v[0:1], v2, off
	v_mov_b32_e32 v0, s93
	v_mov_b32_e32 v1, s17
	v_cndmask_b32_e64 v0, v0, v1, s[4:5]
	v_ashrrev_i32_e32 v1, 31, v0
	v_mul_f32_e32 v2, v54, v17
	v_lshl_add_u64 v[0:1], v[0:1], 2, v[36:37]
	global_store_dword v[0:1], v2, off
	v_mov_b32_e32 v0, s1
	v_mov_b32_e32 v1, s20
	v_cndmask_b32_e64 v0, v0, v1, s[4:5]
	v_ashrrev_i32_e32 v1, 31, v0
	v_mul_f32_e32 v2, v55, v24
	v_lshl_add_u64 v[0:1], v[0:1], 2, v[36:37]
	global_store_dword v[0:1], v2, off
	v_mov_b32_e32 v0, s53
	v_mov_b32_e32 v1, s21
	v_cndmask_b32_e64 v0, v0, v1, s[4:5]
	v_ashrrev_i32_e32 v1, 31, v0
	v_mul_f32_e32 v2, v56, v25
	v_lshl_add_u64 v[0:1], v[0:1], 2, v[36:37]
	global_store_dword v[0:1], v2, off
	v_mov_b32_e32 v0, s0
	v_mov_b32_e32 v1, s22
	v_cndmask_b32_e64 v0, v0, v1, s[4:5]
	v_ashrrev_i32_e32 v1, 31, v0
	v_mul_f32_e32 v2, v57, v40
	v_lshl_add_u64 v[0:1], v[0:1], 2, v[36:37]
	global_store_dword v[0:1], v2, off
	v_mov_b32_e32 v0, s63
	v_mov_b32_e32 v1, s23
	v_cndmask_b32_e64 v0, v0, v1, s[4:5]
	v_ashrrev_i32_e32 v1, 31, v0
	s_add_i32 s6, s6, 1
	s_mov_b64 s[4:5], 0x400
	v_mul_f32_e32 v2, v58, v41
	v_lshl_add_u64 v[0:1], v[0:1], 2, v[36:37]
	v_add_u32_e32 v33, 0x100, v33
	s_cmp_lg_u32 s6, 4
	v_lshl_add_u64 v[34:35], v[34:35], 0, s[4:5]
	global_store_dword v[0:1], v2, off
	s_cbranch_scc1 .LBB0_1110
	v_readlane_b32 s67, v244, 20
	s_add_i32 s45, s45, s67
	v_readlane_b32 s96, v244, 34
	v_readlane_b32 s34, v244, 17
	s_cmpk_lt_i32 s45, 0x110
	v_readlane_b32 s97, v244, 35
	v_readlane_b32 s52, v244, 15
	v_readlane_b32 s35, v244, 18
	v_readlane_b32 s63, v244, 19
	s_movk_i32 s53, 0x440
	v_readlane_b32 s55, v244, 31
	s_cbranch_scc1 .LBB0_1066
